# P3c and P5 epilogues: power-of-two output scale folded into v_cvt_scalef32_pk_fp8_f32 (removes 64/50 v_pk_mul_f32 per unit)
# speedup vs baseline: 1.0046x; 1.0004x over previous
; #define G8_STAGE(bufoff, gbase, NM) do { _Pragma("unroll") for (int _i = 0; _i < 2; ++_i) { \
;     const char* _b = (const char*)(gbase) + (_i ? p2##NM : (size_t)0); asm volatile("" : "+s"(_b));     \
;     __builtin_amdgcn_global_load_lds((const unsigned*)(_b + voff##NM), (LAS unsigned*)(lds + (bufoff) + ldsw + _i * 8192), 16, 0, 0); } } while (0)
; #define G8_WAIT_V(n) asm volatile("s_waitcnt vmcnt(" #n ")" ::: "memory")
; #define G8_BAR __builtin_amdgcn_s_barrier()
;     ...
;   G8_STAGE(G8_SB(0, 0), cB, B); G8_STAGE(G8_SB(0, 1), cB + hstepB, B); G8_STAGE(G8_SA(0, 0), cA, A); G8_STAGE(G8_SA(0, 1), cA + hstepA, A);
;   if (wr == 1) G8_BAR;
;   G8_WAIT_V(2); G8_BAR;
;   G8_STAGE(G8_SB(1, 0), cB + kstep, B); G8_STAGE(G8_SA(1, 0), cA + kstep, A); G8_STAGE(G8_SB(1, 1), cB + hstepB + kstep, B);
;   G8_WAIT_V(6); G8_BAR;
;   __device__ __forceinline__ void operator()(const Acc& acc, const GUnit& u, int wr, int wc, int fr, int fq) const {
;     ...
;         for (int bj = 0; bj < 2; ++bj) { const f32x4 a = acc[ai][bj][m][0] * osc, b = acc[ai][bj][m][1] * osc; u32x2 w;
;           w[0] = __builtin_amdgcn_cvt_pk_fp8_f32(a[0], a[1], 0, false); w[0] = __builtin_amdgcn_cvt_pk_fp8_f32(a[2], a[3], w[0], true);
;           w[1] = __builtin_amdgcn_cvt_pk_fp8_f32(b[0], b[1], 0, false); w[1] = __builtin_amdgcn_cvt_pk_fp8_f32(b[2], b[3], w[1], true);
.LBB0_952:
	s_lshl_b32 s13, s13, 13
	s_ashr_i32 s34, s16, 1
	s_lshl_b32 s14, s14, 13
	s_and_b32 s13, s13, 0x6000
	s_add_u32 s16, s4, 0x80
	s_addc_u32 s17, s5, 0
	s_waitcnt vmcnt(2)
	s_barrier
	s_add_i32 s47, s0, 0x18000
	s_mov_b32 m0, s47
	v_lshl_add_u64 v[2:3], s[16:17], 0, v[198:199]
	s_add_u32 s16, s4, 0x4080
	s_addc_u32 s17, s5, 0
	global_load_lds_dwordx4 v[2:3], off
	s_add_i32 s48, s0, 0x1a000
	v_lshl_add_u64 v[2:3], s[16:17], 0, v[198:199]
	s_add_u32 s16, s8, 0x80
	s_mov_b32 m0, s48
	s_addc_u32 s17, s9, 0
	global_load_lds_dwordx4 v[2:3], off
	s_add_i32 s49, s0, 0x8000
	v_lshl_add_u64 v[2:3], s[16:17], 0, v[196:197]
	s_add_u32 s16, s8, 0x40080
	s_mov_b32 m0, s49
	s_addc_u32 s17, s9, 0
	global_load_lds_dwordx4 v[2:3], off
	s_add_i32 s50, s0, 0xa000
	v_lshl_add_u64 v[2:3], s[16:17], 0, v[196:197]
	s_add_u32 s16, s4, 0x8080
	s_mov_b32 m0, s50
	s_addc_u32 s17, s5, 0
	global_load_lds_dwordx4 v[2:3], off
	s_add_i32 s51, s0, 0x1c000
	s_mov_b32 m0, s51
	v_lshl_add_u64 v[2:3], s[16:17], 0, v[198:199]
	s_add_u32 s16, s4, 0xc080
	s_addc_u32 s17, s5, 0
	s_add_i32 s52, s0, 0x1e000
	global_load_lds_dwordx4 v[2:3], off
	s_mov_b32 m0, s52
	v_lshl_add_u64 v[2:3], s[16:17], 0, v[198:199]
	global_load_lds_dwordx4 v[2:3], off
	v_and_b32_e32 v1, 15, v0
	v_and_b32_e32 v2, 48, v0
	v_lshlrev_b32_e32 v0, 2, v0
	v_lshlrev_b32_e32 v1, 6, v1
	v_and_b32_e32 v0, 32, v0
	v_or_b32_e32 v3, v1, v2
	v_bitop3_b32 v1, v1, v0, v2 bitop3:0x36
	v_or_b32_e32 v1, s13, v1
	s_waitcnt vmcnt(6)
	v_bitop3_b32 v0, v3, s14, v0 bitop3:0xde
	s_cmpk_lt_u32 s12, 0x100
	v_add_u32_e32 v201, 0, v1
	s_cselect_b64 s[12:13], -1, 0
	s_add_i32 s53, s88, s89
	v_add_u32_e32 v202, 0x10000, v201
	v_add_u32_e32 v203, 0x1000, v202
	v_add_u32_e32 v204, 0, v0
	s_mov_b32 s14, 0x41800000
	s_mov_b64 s[16:17], 0x100000
	s_mov_b32 s54, 0x100000
	s_mov_b64 s[18:19], 0x120000
	s_mov_b32 s55, 0x120000
	s_mov_b64 s[20:21], 0x140000
	s_mov_b32 s56, 0x140000
	s_mov_b64 s[22:23], 0x160000
	s_mov_b32 s57, 0x160000
	s_mov_b64 s[28:29], s[8:9]
	s_barrier
	s_branch .LBB0_955

;   __device__ __forceinline__ void operator()(const Acc& acc, const GUnit& u, int wr, int wc, int fr, int fq) const {
;     const int row0 = u.pm * 256 + wr * 64 + fr;
;     unsigned char* ob = Q0 + (size_t)u.pn * 256 + wc * 32 + 8 * fq;
; #pragma unroll
;     for (int ai = 0; ai < 2; ++ai)
; #pragma unroll
;       for (int m = 0; m < 4; ++m) {
;         const int row = row0 + ai * 128 + m * 16;
; #pragma unroll
;         for (int bj = 0; bj < 2; ++bj) { const f32x4 a = acc[ai][bj][m][0] * osc, b = acc[ai][bj][m][1] * osc; u32x2 w;
;           w[0] = __builtin_amdgcn_cvt_pk_fp8_f32(a[0], a[1], 0, false); w[0] = __builtin_amdgcn_cvt_pk_fp8_f32(a[2], a[3], w[0], true);
;           w[1] = __builtin_amdgcn_cvt_pk_fp8_f32(b[0], b[1], 0, false); w[1] = __builtin_amdgcn_cvt_pk_fp8_f32(b[2], b[3], w[1], true);
;           *(u32x2*)(ob + (size_t)row * 8192 + bj * 128) = w; }
;       }
;   }
.LBB0_972:
	v_mov_b32_e32 v0, v200
	s_lshl_b32 s8, s30, 8
	v_readfirstlane_b32 s27, v0
	s_ashr_i32 s9, s27, 2
	s_andn2_b32 s9, s9, 63
	s_add_i32 s9, s9, s8
	v_and_or_b32 v2, v0, 15, s9
	v_lshrrev_b32_e32 v0, 1, v0
	v_and_b32_e32 v64, 24, v0
	v_and_b32_e32 v210, 8, v200
	v_mov_b32_e32 v212, 0x10000
	v_lshl_or_b32 v64, v210, 2, v64
	v_xor_b32_e32 v210, 8, v210
	v_mov_b32_e32 v213, 0
	v_lshl_or_b32 v64, v210, 13, v64
	v_mov_b32_e32 v8, v65
	v_mov_b32_e32 v9, v65
	v_cvt_scalef32_pk_fp8_f32 v8, v192, v193, s14
	v_cvt_scalef32_pk_fp8_f32 v9, v188, v189, s14
	s_ashr_i32 s35, s34, 31
	s_lshl_b64 s[8:9], s[34:35], 8
	v_cvt_scalef32_pk_fp8_f32 v8, v194, v195, s14 op_sel:[0,0,0,1]
	v_cvt_scalef32_pk_fp8_f32 v9, v190, v191, s14 op_sel:[0,0,0,1]
	v_mov_b32_e32 v10, v65
	v_mov_b32_e32 v11, v65
	s_add_u32 s8, s92, s8
	v_cvt_scalef32_pk_fp8_f32 v10, v184, v185, s14
	v_cvt_scalef32_pk_fp8_f32 v11, v180, v181, s14
	s_addc_u32 s9, s93, s9
	s_and_b32 s27, s27, 0xc0
	s_add_u32 s8, s8, s27
	s_addc_u32 s9, s9, 0
	s_sub_u32 s8, s8, 0x10000
	s_subb_u32 s9, s9, 0
	v_ashrrev_i32_e32 v3, 31, v2
	v_cvt_scalef32_pk_fp8_f32 v10, v186, v187, s14 op_sel:[0,0,0,1]
	v_cvt_scalef32_pk_fp8_f32 v11, v182, v183, s14 op_sel:[0,0,0,1]
	v_lshl_add_u64 v[4:5], s[8:9], 0, v[64:65]
	v_lshlrev_b64 v[0:1], 13, v[2:3]
	v_lshl_add_u64 v[0:1], v[4:5], 0, v[0:1]
	v_mov_b32_e32 v214, v8
	v_mov_b32_e32 v215, v9
	v_mov_b32_dpp v8, v10 row_ror:8 row_mask:0xf bank_mask:0xc
	v_mov_b32_dpp v9, v11 row_ror:8 row_mask:0xf bank_mask:0xc
	v_mov_b32_dpp v10, v214 row_ror:8 row_mask:0xf bank_mask:0x3
	v_mov_b32_dpp v11, v215 row_ror:8 row_mask:0xf bank_mask:0x3
	v_lshl_add_u64 v[216:217], v[0:1], 0, v[212:213]
	global_store_dwordx2 v[0:1], v[8:9], off
	global_store_dwordx2 v[216:217], v[10:11], off
	v_mov_b32_e32 v12, v65
	v_mov_b32_e32 v13, v65
	v_cvt_scalef32_pk_fp8_f32 v12, v160, v161, s14
	v_cvt_scalef32_pk_fp8_f32 v13, v156, v157, s14
	v_cvt_scalef32_pk_fp8_f32 v12, v162, v163, s14 op_sel:[0,0,0,1]
	v_cvt_scalef32_pk_fp8_f32 v13, v158, v159, s14 op_sel:[0,0,0,1]
	v_mov_b32_e32 v14, v65
	v_mov_b32_e32 v15, v65
	v_cvt_scalef32_pk_fp8_f32 v14, v152, v153, s14
	v_cvt_scalef32_pk_fp8_f32 v15, v148, v149, s14
	v_or_b32_e32 v6, 16, v2
	v_ashrrev_i32_e32 v7, 31, v6
	v_cvt_scalef32_pk_fp8_f32 v14, v154, v155, s14 op_sel:[0,0,0,1]
	v_cvt_scalef32_pk_fp8_f32 v15, v150, v151, s14 op_sel:[0,0,0,1]
	v_lshlrev_b64 v[6:7], 13, v[6:7]
	v_lshl_add_u64 v[6:7], v[4:5], 0, v[6:7]
	v_mov_b32_e32 v214, v12
	v_mov_b32_e32 v215, v13
	v_mov_b32_dpp v12, v14 row_ror:8 row_mask:0xf bank_mask:0xc
	v_mov_b32_dpp v13, v15 row_ror:8 row_mask:0xf bank_mask:0xc
	v_mov_b32_dpp v14, v214 row_ror:8 row_mask:0xf bank_mask:0x3
	v_mov_b32_dpp v15, v215 row_ror:8 row_mask:0xf bank_mask:0x3
	v_lshl_add_u64 v[216:217], v[6:7], 0, v[212:213]
	global_store_dwordx2 v[6:7], v[12:13], off
	global_store_dwordx2 v[216:217], v[14:15], off
	v_mov_b32_e32 v12, v65
	v_mov_b32_e32 v13, v65
	v_cvt_scalef32_pk_fp8_f32 v12, v128, v129, s14
	v_cvt_scalef32_pk_fp8_f32 v13, v124, v125, s14
	v_cvt_scalef32_pk_fp8_f32 v12, v130, v131, s14 op_sel:[0,0,0,1]
	v_cvt_scalef32_pk_fp8_f32 v13, v126, v127, s14 op_sel:[0,0,0,1]
	v_mov_b32_e32 v14, v65
	v_mov_b32_e32 v15, v65
	v_cvt_scalef32_pk_fp8_f32 v14, v120, v121, s14
	v_cvt_scalef32_pk_fp8_f32 v15, v116, v117, s14
	v_or_b32_e32 v6, 32, v2
	v_ashrrev_i32_e32 v7, 31, v6
	v_cvt_scalef32_pk_fp8_f32 v14, v122, v123, s14 op_sel:[0,0,0,1]
	v_cvt_scalef32_pk_fp8_f32 v15, v118, v119, s14 op_sel:[0,0,0,1]
	v_lshlrev_b64 v[6:7], 13, v[6:7]
	v_lshl_add_u64 v[6:7], v[4:5], 0, v[6:7]
	v_mov_b32_e32 v214, v12
	v_mov_b32_e32 v215, v13
	v_mov_b32_dpp v12, v14 row_ror:8 row_mask:0xf bank_mask:0xc
	v_mov_b32_dpp v13, v15 row_ror:8 row_mask:0xf bank_mask:0xc
	v_mov_b32_dpp v14, v214 row_ror:8 row_mask:0xf bank_mask:0x3
	v_mov_b32_dpp v15, v215 row_ror:8 row_mask:0xf bank_mask:0x3
	v_lshl_add_u64 v[216:217], v[6:7], 0, v[212:213]
	global_store_dwordx2 v[6:7], v[12:13], off
	global_store_dwordx2 v[216:217], v[14:15], off
	v_mov_b32_e32 v10, v65
	v_mov_b32_e32 v11, v65
	v_cvt_scalef32_pk_fp8_f32 v10, v96, v97, s14
	v_cvt_scalef32_pk_fp8_f32 v11, v92, v93, s14
	v_cvt_scalef32_pk_fp8_f32 v10, v98, v99, s14 op_sel:[0,0,0,1]
	v_cvt_scalef32_pk_fp8_f32 v11, v94, v95, s14 op_sel:[0,0,0,1]
	v_mov_b32_e32 v12, v65
	v_mov_b32_e32 v13, v65
	v_cvt_scalef32_pk_fp8_f32 v12, v88, v89, s14
	v_cvt_scalef32_pk_fp8_f32 v13, v84, v85, s14
	v_or_b32_e32 v2, 48, v2
	v_ashrrev_i32_e32 v3, 31, v2
	v_lshlrev_b64 v[2:3], 13, v[2:3]
	v_cvt_scalef32_pk_fp8_f32 v12, v90, v91, s14 op_sel:[0,0,0,1]
	v_cvt_scalef32_pk_fp8_f32 v13, v86, v87, s14 op_sel:[0,0,0,1]
	v_lshl_add_u64 v[2:3], v[4:5], 0, v[2:3]
	v_mov_b32_e32 v8, v65
	v_mov_b32_e32 v9, v65
	v_cvt_scalef32_pk_fp8_f32 v8, v176, v177, s14
	v_cvt_scalef32_pk_fp8_f32 v9, v172, v173, s14
	v_mov_b32_e32 v214, v10
;   __device__ __forceinline__ void operator()(const Acc& acc, const GUnit& u, int wr, int wc, int fr, int fq) const {
;     const int row0 = u.pm * 256 + wr * 64 + fr;
;     unsigned char* ob = Q0 + (size_t)u.pn * 256 + wc * 32 + 8 * fq;
; #pragma unroll
;     for (int ai = 0; ai < 2; ++ai)
; #pragma unroll
;       for (int m = 0; m < 4; ++m) {
;         const int row = row0 + ai * 128 + m * 16;
; #pragma unroll
;         for (int bj = 0; bj < 2; ++bj) { const f32x4 a = acc[ai][bj][m][0] * osc, b = acc[ai][bj][m][1] * osc; u32x2 w;
;           w[0] = __builtin_amdgcn_cvt_pk_fp8_f32(a[0], a[1], 0, false); w[0] = __builtin_amdgcn_cvt_pk_fp8_f32(a[2], a[3], w[0], true);
;           w[1] = __builtin_amdgcn_cvt_pk_fp8_f32(b[0], b[1], 0, false); w[1] = __builtin_amdgcn_cvt_pk_fp8_f32(b[2], b[3], w[1], true);
;           *(u32x2*)(ob + (size_t)row * 8192 + bj * 128) = w; }
;       }
;   }
	v_mov_b32_e32 v215, v11
	v_mov_b32_dpp v10, v12 row_ror:8 row_mask:0xf bank_mask:0xc
	v_mov_b32_dpp v11, v13 row_ror:8 row_mask:0xf bank_mask:0xc
	v_mov_b32_dpp v12, v214 row_ror:8 row_mask:0xf bank_mask:0x3
	v_mov_b32_dpp v13, v215 row_ror:8 row_mask:0xf bank_mask:0x3
	v_lshl_add_u64 v[216:217], v[2:3], 0, v[212:213]
	global_store_dwordx2 v[2:3], v[10:11], off
	global_store_dwordx2 v[216:217], v[12:13], off
	v_cvt_scalef32_pk_fp8_f32 v8, v178, v179, s14 op_sel:[0,0,0,1]
	v_cvt_scalef32_pk_fp8_f32 v9, v174, v175, s14 op_sel:[0,0,0,1]
	v_mov_b32_e32 v10, v65
	v_mov_b32_e32 v11, v65
	v_cvt_scalef32_pk_fp8_f32 v10, v168, v169, s14
	v_cvt_scalef32_pk_fp8_f32 v11, v164, v165, s14
	v_cvt_scalef32_pk_fp8_f32 v10, v170, v171, s14 op_sel:[0,0,0,1]
	v_cvt_scalef32_pk_fp8_f32 v11, v166, v167, s14 op_sel:[0,0,0,1]
	v_add_co_u32_e32 v4, vcc, s54, v0
	v_lshl_add_u64 v[2:3], v[0:1], 0, s[16:17]
	s_nop 0
	v_addc_co_u32_e32 v5, vcc, 0, v1, vcc
	v_mov_b32_e32 v214, v8
	v_mov_b32_e32 v215, v9
	v_mov_b32_dpp v8, v10 row_ror:8 row_mask:0xf bank_mask:0xc
	v_mov_b32_dpp v9, v11 row_ror:8 row_mask:0xf bank_mask:0xc
	v_mov_b32_dpp v10, v214 row_ror:8 row_mask:0xf bank_mask:0x3
	v_mov_b32_dpp v11, v215 row_ror:8 row_mask:0xf bank_mask:0x3
	v_lshl_add_u64 v[216:217], v[4:5], 0, v[212:213]
	global_store_dwordx2 v[4:5], v[8:9], off
	global_store_dwordx2 v[216:217], v[10:11], off
	v_mov_b32_e32 v8, v65
	v_mov_b32_e32 v9, v65
	v_cvt_scalef32_pk_fp8_f32 v8, v144, v145, s14
	v_cvt_scalef32_pk_fp8_f32 v9, v140, v141, s14
	v_cvt_scalef32_pk_fp8_f32 v8, v146, v147, s14 op_sel:[0,0,0,1]
	v_cvt_scalef32_pk_fp8_f32 v9, v142, v143, s14 op_sel:[0,0,0,1]
	v_mov_b32_e32 v10, v65
	v_mov_b32_e32 v11, v65
	v_cvt_scalef32_pk_fp8_f32 v10, v136, v137, s14
	v_cvt_scalef32_pk_fp8_f32 v11, v132, v133, s14
	v_cvt_scalef32_pk_fp8_f32 v10, v138, v139, s14 op_sel:[0,0,0,1]
	v_cvt_scalef32_pk_fp8_f32 v11, v134, v135, s14 op_sel:[0,0,0,1]
	v_add_co_u32_e32 v4, vcc, s55, v0
	v_lshl_add_u64 v[2:3], v[0:1], 0, s[18:19]
	s_nop 0
	v_addc_co_u32_e32 v5, vcc, 0, v1, vcc
	v_mov_b32_e32 v214, v8
	v_mov_b32_e32 v215, v9
	v_mov_b32_dpp v8, v10 row_ror:8 row_mask:0xf bank_mask:0xc
	v_mov_b32_dpp v9, v11 row_ror:8 row_mask:0xf bank_mask:0xc
	v_mov_b32_dpp v10, v214 row_ror:8 row_mask:0xf bank_mask:0x3
	v_mov_b32_dpp v11, v215 row_ror:8 row_mask:0xf bank_mask:0x3
	v_lshl_add_u64 v[216:217], v[4:5], 0, v[212:213]
	global_store_dwordx2 v[4:5], v[8:9], off
	global_store_dwordx2 v[216:217], v[10:11], off
	v_mov_b32_e32 v8, v65
	v_mov_b32_e32 v9, v65
	v_cvt_scalef32_pk_fp8_f32 v8, v112, v113, s14
	v_cvt_scalef32_pk_fp8_f32 v9, v108, v109, s14
	v_cvt_scalef32_pk_fp8_f32 v8, v114, v115, s14 op_sel:[0,0,0,1]
	v_cvt_scalef32_pk_fp8_f32 v9, v110, v111, s14 op_sel:[0,0,0,1]
	v_mov_b32_e32 v10, v65
	v_mov_b32_e32 v11, v65
	v_cvt_scalef32_pk_fp8_f32 v10, v104, v105, s14
	v_cvt_scalef32_pk_fp8_f32 v11, v100, v101, s14
	v_cvt_scalef32_pk_fp8_f32 v10, v106, v107, s14 op_sel:[0,0,0,1]
	v_cvt_scalef32_pk_fp8_f32 v11, v102, v103, s14 op_sel:[0,0,0,1]
	v_add_co_u32_e32 v4, vcc, s56, v0
	v_lshl_add_u64 v[2:3], v[0:1], 0, s[20:21]
	s_nop 0
	v_addc_co_u32_e32 v5, vcc, 0, v1, vcc
	v_mov_b32_e32 v214, v8
	v_mov_b32_e32 v215, v9
	v_mov_b32_dpp v8, v10 row_ror:8 row_mask:0xf bank_mask:0xc
	v_mov_b32_dpp v9, v11 row_ror:8 row_mask:0xf bank_mask:0xc
	v_mov_b32_dpp v10, v214 row_ror:8 row_mask:0xf bank_mask:0x3
	v_mov_b32_dpp v11, v215 row_ror:8 row_mask:0xf bank_mask:0x3
	v_lshl_add_u64 v[216:217], v[4:5], 0, v[212:213]
	global_store_dwordx2 v[4:5], v[8:9], off
	global_store_dwordx2 v[216:217], v[10:11], off
	v_mov_b32_e32 v8, v65
	v_mov_b32_e32 v9, v65
	v_cvt_scalef32_pk_fp8_f32 v8, v80, v81, s14
	v_cvt_scalef32_pk_fp8_f32 v9, v76, v77, s14
	v_cvt_scalef32_pk_fp8_f32 v8, v82, v83, s14 op_sel:[0,0,0,1]
	v_cvt_scalef32_pk_fp8_f32 v9, v78, v79, s14 op_sel:[0,0,0,1]
	v_mov_b32_e32 v10, v65
	v_mov_b32_e32 v11, v65
	v_cvt_scalef32_pk_fp8_f32 v10, v72, v73, s14
	v_cvt_scalef32_pk_fp8_f32 v11, v68, v69, s14
	v_lshl_add_u64 v[2:3], v[0:1], 0, s[22:23]
	v_cvt_scalef32_pk_fp8_f32 v10, v74, v75, s14 op_sel:[0,0,0,1]
	v_cvt_scalef32_pk_fp8_f32 v11, v70, v71, s14 op_sel:[0,0,0,1]
	v_add_co_u32_e32 v0, vcc, s57, v0
	s_mov_b64 s[8:9], -1
	s_nop 0
	v_addc_co_u32_e32 v1, vcc, 0, v1, vcc
	s_andn2_b64 vcc, exec, s[24:25]
	v_mov_b32_e32 v214, v8
	v_mov_b32_e32 v215, v9
	v_mov_b32_dpp v8, v10 row_ror:8 row_mask:0xf bank_mask:0xc
	v_mov_b32_dpp v9, v11 row_ror:8 row_mask:0xf bank_mask:0xc
	v_mov_b32_dpp v10, v214 row_ror:8 row_mask:0xf bank_mask:0x3
	v_mov_b32_dpp v11, v215 row_ror:8 row_mask:0xf bank_mask:0x3
	v_lshl_add_u64 v[216:217], v[0:1], 0, v[212:213]
	global_store_dwordx2 v[0:1], v[8:9], off
	global_store_dwordx2 v[216:217], v[10:11], off
	s_cbranch_vccnz .LBB0_954
	s_andn2_b64 vcc, exec, s[10:11]
	s_cbranch_vccnz .LBB0_953
	s_barrier
	s_branch .LBB0_953

; #define G8_STAGE(bufoff, gbase, NM) do { _Pragma("unroll") for (int _i = 0; _i < 2; ++_i) { \
;     const char* _b = (const char*)(gbase) + (_i ? p2##NM : (size_t)0); asm volatile("" : "+s"(_b));     \
;     __builtin_amdgcn_global_load_lds((const unsigned*)(_b + voff##NM), (LAS unsigned*)(lds + (bufoff) + ldsw + _i * 8192), 16, 0, 0); } } while (0)
; #define G8_WAIT_V(n) asm volatile("s_waitcnt vmcnt(" #n ")" ::: "memory")
; #define G8_BAR __builtin_amdgcn_s_barrier()
;     ...
;   G8_STAGE(G8_SB(0, 0), cB, B); G8_STAGE(G8_SB(0, 1), cB + hstepB, B); G8_STAGE(G8_SA(0, 0), cA, A); G8_STAGE(G8_SA(0, 1), cA + hstepA, A);
;   if (wr == 1) G8_BAR;
;   G8_WAIT_V(2); G8_BAR;
;   G8_STAGE(G8_SB(1, 0), cB + kstep, B); G8_STAGE(G8_SA(1, 0), cA + kstep, A); G8_STAGE(G8_SB(1, 1), cB + hstepB + kstep, B);
;   G8_WAIT_V(6); G8_BAR;
; __global__ void __launch_bounds__(512, 2) fwd_mega(Params p) {
;     ...
;   REPS(5) {
;     g8::Sched S; S.init(128, 16, nb, bid); S.A0 = (const char*)(ws + OFF_QL0); S.sAm = (size_t)256 * 8192; S.sAn = 512; S.B0 = (const char*)(ws + OFF_WUV); S.sBn = (size_t)256 * 512;
;     g8::EpiGate E{ws + OFF_RQ, ws + OFF_RZ, 16.f / 256.f};
;     g8::gemm_phase<g8::EpiGate, true, 1>(gl, 256, 4096, 256, S, E);
;   }
.LBB0_1035:
	s_lshl_b32 s12, s12, 12
	s_lshl_b32 s16, s14, 13
	s_and_b32 s12, s12, 0x3000
	s_add_u32 s14, s36, 0x80
	s_addc_u32 s15, s37, 0
	s_waitcnt vmcnt(2)
	s_barrier
	s_add_i32 m0, s1, 0x18000
	v_and_b32_e32 v1, 15, v0
	v_lshl_add_u64 v[2:3], s[14:15], 0, v[130:131]
	s_add_u32 s14, s36, 0x8080
	s_addc_u32 s15, s37, 0
	global_load_lds_dwordx4 v[2:3], off
	s_add_i32 m0, s1, 0x1a000
	v_lshl_add_u64 v[2:3], s[14:15], 0, v[130:131]
	s_add_u32 s14, s30, 0x80
	s_addc_u32 s15, s31, 0
	global_load_lds_dwordx4 v[2:3], off
	s_add_i32 s29, s1, 0x8000
	v_lshl_add_u64 v[2:3], s[14:15], 0, v[128:129]
	s_add_u32 s14, s30, 0x80080
	s_mov_b32 m0, s29
	s_addc_u32 s15, s31, 0
	global_load_lds_dwordx4 v[2:3], off
	s_add_i32 s33, s1, 0xa000
	v_lshl_add_u64 v[2:3], s[14:15], 0, v[128:129]
	s_add_u32 s14, s36, 0x10080
	s_mov_b32 m0, s33
	s_addc_u32 s15, s37, 0
	global_load_lds_dwordx4 v[2:3], off
	s_add_i32 m0, s1, 0x1c000
	v_lshlrev_b32_e32 v1, 6, v1
	v_lshl_add_u64 v[2:3], s[14:15], 0, v[130:131]
	s_add_u32 s14, s36, 0x18080
	s_addc_u32 s15, s37, 0
	global_load_lds_dwordx4 v[2:3], off
	s_add_i32 m0, s1, 0x1e000
	v_lshl_add_u64 v[2:3], s[14:15], 0, v[130:131]
	global_load_lds_dwordx4 v[2:3], off
	v_and_b32_e32 v2, 48, v0
	v_lshlrev_b32_e32 v0, 2, v0
	v_and_b32_e32 v0, 32, v0
	v_or_b32_e32 v3, v1, v2
	v_bitop3_b32 v1, v1, v0, v2 bitop3:0x36
	s_waitcnt vmcnt(6)
	s_cmpk_lt_u32 s11, 0x100
	s_sext_i32_i8 s46, s10
	v_bitop3_b32 v0, v3, s16, v0 bitop3:0xde
	v_or_b32_e32 v138, s12, v1
	s_cselect_b64 s[10:11], -1, 0
	s_add_i32 s43, 0, 0x10000
	s_add_i32 s44, 0, 0x14000
	s_add_i32 s42, s88, s89
	v_add_u32_e32 v139, s43, v138
	v_add_u32_e32 v140, 0, v0
	v_add_u32_e32 v141, s44, v138
	s_mov_b32 s12, 0x41800000
	s_mov_b64 s[14:15], 0x90000
	s_mov_b64 s[16:17], 0xa0000
	s_mov_b64 s[18:19], 0xb0000
	s_barrier
	s_branch .LBB0_1038

; __device__ __forceinline__ float silu_fast(float z) { return z * __builtin_amdgcn_rcpf(1.f + __builtin_amdgcn_exp2f(-1.4426950408889634f * z)); }
;   __device__ __forceinline__ void operator()(const Acc& acc, const GUnit& u, int wr, int wc, int fr, int fq) const {
;     const int row0 = u.pm * 256 + wr * 64 + fr; const int col0 = u.pn * 256 + wc * 32 + 8 * fq;
; #pragma unroll
;     for (int ai = 0; ai < 2; ++ai)
; #pragma unroll
;       for (int m = 0; m < 4; ++m) {
;         const size_t off = (size_t)(row0 + ai * 128 + m * 16) * 4096 + col0;
; #pragma unroll
;         for (int bj = 0; bj < 2; ++bj) {
;           const u32x2 zw = *(const u32x2*)(Z + off + bj * 128);
;           typedef float f32x2v __attribute__((ext_vector_type(2)));
;           const f32x2v z0 = __builtin_amdgcn_cvt_pk_f32_fp8(zw[0], false), z1 = __builtin_amdgcn_cvt_pk_f32_fp8(zw[0], true), z2 = __builtin_amdgcn_cvt_pk_f32_fp8(zw[1], false), z3 = __builtin_amdgcn_cvt_pk_f32_fp8(zw[1], true);
;           f32x4 a = acc[ai][bj][m][0] * osc, b = acc[ai][bj][m][1] * osc;
;           a[0] *= silu_fast(z0[0]); a[1] *= silu_fast(z0[1]); a[2] *= silu_fast(z1[0]); a[3] *= silu_fast(z1[1]);
;           b[0] *= silu_fast(z2[0]); b[1] *= silu_fast(z2[1]); b[2] *= silu_fast(z3[0]); b[3] *= silu_fast(z3[1]);
;           u32x2 w; w[0] = __builtin_amdgcn_cvt_pk_fp8_f32(a[0], a[1], 0, false); w[0] = __builtin_amdgcn_cvt_pk_fp8_f32(a[2], a[3], w[0], true);
;           w[1] = __builtin_amdgcn_cvt_pk_fp8_f32(b[0], b[1], 0, false); w[1] = __builtin_amdgcn_cvt_pk_fp8_f32(b[2], b[3], w[1], true);
;           *(u32x2*)(Y + off + bj * 128) = w;
;         }
.LBB0_1047:
	v_mov_b32_e32 v132, v200
	s_lshl_b32 s28, s28, 8
	v_readfirstlane_b32 s23, v132
	s_ashr_i32 s30, s23, 2
	s_andn2_b32 s30, s30, 63
	s_lshr_b32 s23, s23, 1
	s_add_i32 s30, s30, s28
	s_lshl_b32 s28, s46, 8
	s_and_b32 s23, s23, 0x60
	v_and_or_b32 v134, v132, 15, s30
	s_or_b32 s23, s23, s28
	v_lshrrev_b32_e32 v132, 1, v132
	v_and_or_b32 v136, v132, 24, s23
	v_ashrrev_i32_e32 v135, 31, v134
	v_ashrrev_i32_e32 v137, 31, v136
	v_lshlrev_b64 v[132:133], 12, v[134:135]
	v_readlane_b32 s30, v254, 38
	v_lshl_add_u64 v[132:133], v[132:133], 0, v[136:137]
	v_readlane_b32 s31, v254, 39
	v_mov_b32_e32 v147, 0
	v_lshl_add_u64 v[142:143], s[30:31], 0, v[132:133]
	global_load_dwordx2 v[144:145], v[142:143], off
	s_nop 0
	global_load_dwordx2 v[142:143], v[142:143], off offset:128
	v_mov_b32_e32 v146, 0
	v_readlane_b32 s36, v254, 16
	v_readlane_b32 s38, v254, 18
	v_readlane_b32 s39, v254, 19
	s_andn2_b64 vcc, exec, s[20:21]
	s_mov_b64 s[20:21], -1
	v_readlane_b32 s37, v254, 17
	s_waitcnt vmcnt(0)
	v_cvt_pk_f32_fp8_e32 v[148:149], v144
	v_cvt_pk_f32_fp8_sdwa v[150:151], v144 src0_sel:WORD_1
	v_cvt_pk_f32_fp8_e32 v[152:153], v145
	v_cvt_pk_f32_fp8_sdwa v[144:145], v145 src0_sel:WORD_1
	v_mul_f32_e32 v135, 0xbfb8aa3b, v148
	v_mul_f32_e32 v160, 0xbfb8aa3b, v149
	v_mul_f32_e32 v161, 0xbfb8aa3b, v150
	v_mul_f32_e32 v162, 0xbfb8aa3b, v151
	v_mul_f32_e32 v163, 0xbfb8aa3b, v152
	v_mul_f32_e32 v164, 0xbfb8aa3b, v153
	v_exp_f32_e32 v135, v135
	v_exp_f32_e32 v160, v160
	v_exp_f32_e32 v161, v161
	v_exp_f32_e32 v162, v162
	v_exp_f32_e32 v163, v163
	v_exp_f32_e32 v164, v164
	v_mul_f32_e32 v165, 0xbfb8aa3b, v144
	v_mul_f32_e32 v166, 0xbfb8aa3b, v145
	v_exp_f32_e32 v165, v165
	v_exp_f32_e32 v166, v166
	v_add_f32_e32 v135, 1.0, v135
	v_add_f32_e32 v160, 1.0, v160
	v_add_f32_e32 v161, 1.0, v161
	v_add_f32_e32 v162, 1.0, v162
	v_add_f32_e32 v163, 1.0, v163
	v_add_f32_e32 v164, 1.0, v164
	v_cvt_pk_f32_fp8_sdwa v[156:157], v142 src0_sel:WORD_1
	v_rcp_f32_e32 v135, v135
	v_rcp_f32_e32 v160, v160
	v_rcp_f32_e32 v161, v161
	v_rcp_f32_e32 v162, v162
	v_rcp_f32_e32 v163, v163
	v_rcp_f32_e32 v164, v164
	v_add_f32_e32 v165, 1.0, v165
	v_add_f32_e32 v166, 1.0, v166
	v_mul_f32_e32 v170, 0xbfb8aa3b, v157
	v_rcp_f32_e32 v165, v165
	v_rcp_f32_e32 v166, v166
	v_mul_f32_e32 v135, v148, v135
	v_mul_f32_e32 v148, v149, v160
	v_mul_f32_e32 v149, v150, v161
	v_mul_f32_e32 v150, v151, v162
	v_mul_f32_e32 v151, v152, v163
	v_mul_f32_e32 v152, v153, v164
	v_exp_f32_e32 v170, v170
	v_mul_f32_e32 v104, v104, v151
	v_mul_f32_e32 v105, v105, v152
	v_cvt_pk_f32_fp8_e32 v[158:159], v143
	v_cvt_scalef32_pk_fp8_f32 v147, v104, v105, s12
	v_mul_f32_e32 v144, v144, v165
	v_mul_f32_e32 v145, v145, v166
	v_add_f32_e32 v170, 1.0, v170
	v_mul_f32_e32 v106, v106, v144
	v_mul_f32_e32 v107, v107, v145
	v_rcp_f32_e32 v170, v170
	v_mul_f32_e32 v108, v108, v135
	v_mul_f32_e32 v109, v109, v148
	v_cvt_scalef32_pk_fp8_f32 v147, v106, v107, s12 op_sel:[0,0,0,1]
	v_mul_f32_e32 v107, 0xbfb8aa3b, v158
	v_cvt_scalef32_pk_fp8_f32 v146, v108, v109, s12
	v_exp_f32_e32 v107, v107
	v_mul_f32_e32 v109, 0xbfb8aa3b, v159
	v_cvt_pk_f32_fp8_e32 v[154:155], v142
	v_cvt_pk_f32_fp8_sdwa v[142:143], v143 src0_sel:WORD_1
	v_exp_f32_e32 v109, v109
	v_mul_f32_e32 v110, v110, v149
	v_mul_f32_e32 v111, v111, v150
	v_mul_f32_e32 v104, v157, v170
	v_cvt_scalef32_pk_fp8_f32 v146, v110, v111, s12 op_sel:[0,0,0,1]
	v_mul_f32_e32 v110, v127, v104
	v_add_f32_e32 v104, 1.0, v107
	v_rcp_f32_e32 v104, v104
	v_add_f32_e32 v107, 1.0, v109
	v_mul_f32_e32 v109, 0xbfb8aa3b, v142
	v_mul_f32_e32 v167, 0xbfb8aa3b, v154
	v_mul_f32_e32 v168, 0xbfb8aa3b, v155
	v_rcp_f32_e32 v107, v107
	v_exp_f32_e32 v109, v109
	v_exp_f32_e32 v167, v167
	v_exp_f32_e32 v168, v168
	v_mul_f32_e32 v104, v158, v104
	v_mul_f32_e32 v111, v120, v104
	v_mul_f32_e32 v104, v159, v107
	v_add_f32_e32 v107, 1.0, v109
	v_mul_f32_e32 v169, 0xbfb8aa3b, v156
	v_add_f32_e32 v167, 1.0, v167
	v_add_f32_e32 v168, 1.0, v168
	v_rcp_f32_e32 v107, v107
	v_mul_f32_e32 v109, 0xbfb8aa3b, v143
	v_exp_f32_e32 v169, v169
	v_rcp_f32_e32 v167, v167
	v_rcp_f32_e32 v168, v168
	v_exp_f32_e32 v109, v109
	v_mul_f32_e32 v120, v121, v104
	v_mul_f32_e32 v104, v142, v107
	v_add_f32_e32 v169, 1.0, v169
	v_mul_f32_e32 v153, v154, v167
	v_mul_f32_e32 v154, v155, v168
	v_mul_f32_e32 v107, v122, v104
	v_add_f32_e32 v104, 1.0, v109
	v_rcp_f32_e32 v169, v169
	v_mul_f32_e32 v105, v124, v153
	v_mul_f32_e32 v108, v125, v154
	v_rcp_f32_e32 v109, v104
	v_mov_b32_e32 v104, 0
	v_cvt_scalef32_pk_fp8_f32 v104, v105, v108, s12
	v_mov_b32_e32 v105, 0
	v_cvt_scalef32_pk_fp8_f32 v105, v111, v120, s12
	v_mul_f32_e32 v155, v156, v169
	v_mul_f32_e32 v108, v143, v109
	v_mul_f32_e32 v106, v126, v155
	v_mul_f32_e32 v108, v123, v108
	v_cvt_scalef32_pk_fp8_f32 v104, v106, v110, s12 op_sel:[0,0,0,1]
	v_cvt_scalef32_pk_fp8_f32 v105, v107, v108, s12 op_sel:[0,0,0,1]
	v_lshl_add_u64 v[106:107], s[38:39], 0, v[132:133]
	global_store_dwordx2 v[106:107], v[146:147], off
	global_store_dwordx2 v[106:107], v[104:105], off offset:128
	v_or_b32_e32 v104, 16, v134
	v_ashrrev_i32_e32 v105, 31, v104
	v_lshlrev_b64 v[104:105], 12, v[104:105]
	v_lshl_add_u64 v[104:105], v[104:105], 0, v[136:137]
	v_lshl_add_u64 v[106:107], s[30:31], 0, v[104:105]
	global_load_dwordx2 v[108:109], v[106:107], off
	s_nop 0
	global_load_dwordx2 v[106:107], v[106:107], off offset:128
	v_mov_b32_e32 v111, 0
	v_mov_b32_e32 v110, 0
	s_waitcnt vmcnt(1)
; __device__ __forceinline__ float silu_fast(float z) { return z * __builtin_amdgcn_rcpf(1.f + __builtin_amdgcn_exp2f(-1.4426950408889634f * z)); }
;   __device__ __forceinline__ void operator()(const Acc& acc, const GUnit& u, int wr, int wc, int fr, int fq) const {
;     ...
;       for (int m = 0; m < 4; ++m) {
;         const size_t off = (size_t)(row0 + ai * 128 + m * 16) * 4096 + col0;
; #pragma unroll
;         for (int bj = 0; bj < 2; ++bj) {
;           const u32x2 zw = *(const u32x2*)(Z + off + bj * 128);
;           typedef float f32x2v __attribute__((ext_vector_type(2)));
;           const f32x2v z0 = __builtin_amdgcn_cvt_pk_f32_fp8(zw[0], false), z1 = __builtin_amdgcn_cvt_pk_f32_fp8(zw[0], true), z2 = __builtin_amdgcn_cvt_pk_f32_fp8(zw[1], false), z3 = __builtin_amdgcn_cvt_pk_f32_fp8(zw[1], true);
;           f32x4 a = acc[ai][bj][m][0] * osc, b = acc[ai][bj][m][1] * osc;
;           a[0] *= silu_fast(z0[0]); a[1] *= silu_fast(z0[1]); a[2] *= silu_fast(z1[0]); a[3] *= silu_fast(z1[1]);
;           b[0] *= silu_fast(z2[0]); b[1] *= silu_fast(z2[1]); b[2] *= silu_fast(z3[0]); b[3] *= silu_fast(z3[1]);
;           u32x2 w; w[0] = __builtin_amdgcn_cvt_pk_fp8_f32(a[0], a[1], 0, false); w[0] = __builtin_amdgcn_cvt_pk_fp8_f32(a[2], a[3], w[0], true);
;           w[1] = __builtin_amdgcn_cvt_pk_fp8_f32(b[0], b[1], 0, false); w[1] = __builtin_amdgcn_cvt_pk_fp8_f32(b[2], b[3], w[1], true);
;           *(u32x2*)(Y + off + bj * 128) = w;
;         }
	v_cvt_pk_f32_fp8_e32 v[124:125], v109
	v_cvt_pk_f32_fp8_e32 v[120:121], v108
	v_cvt_pk_f32_fp8_sdwa v[122:123], v108 src0_sel:WORD_1
	v_cvt_pk_f32_fp8_sdwa v[108:109], v109 src0_sel:WORD_1
	v_mul_f32_e32 v143, 0xbfb8aa3b, v124
	v_mul_f32_e32 v144, 0xbfb8aa3b, v125
	v_exp_f32_e32 v143, v143
	v_exp_f32_e32 v144, v144
	v_mul_f32_e32 v145, 0xbfb8aa3b, v108
	v_mul_f32_e32 v146, 0xbfb8aa3b, v109
	v_exp_f32_e32 v145, v145
	v_exp_f32_e32 v146, v146
	v_add_f32_e32 v143, 1.0, v143
	v_add_f32_e32 v144, 1.0, v144
	v_rcp_f32_e32 v143, v143
	v_rcp_f32_e32 v144, v144
	v_add_f32_e32 v145, 1.0, v145
	v_add_f32_e32 v146, 1.0, v146
	v_mul_f32_e32 v126, 0xbfb8aa3b, v120
	v_rcp_f32_e32 v145, v145
	v_rcp_f32_e32 v146, v146
	v_mul_f32_e32 v124, v124, v143
	v_mul_f32_e32 v125, v125, v144
	v_exp_f32_e32 v126, v126
	v_mul_f32_e32 v88, v88, v124
	v_mul_f32_e32 v89, v89, v125
	v_cvt_scalef32_pk_fp8_f32 v111, v88, v89, s12
	v_mul_f32_e32 v108, v108, v145
	v_mul_f32_e32 v109, v109, v146
	v_add_f32_e32 v126, 1.0, v126
	v_mul_f32_e32 v88, v90, v108
	v_mul_f32_e32 v89, v91, v109
	v_rcp_f32_e32 v126, v126
	v_cvt_scalef32_pk_fp8_f32 v111, v88, v89, s12 op_sel:[0,0,0,1]
	s_waitcnt vmcnt(0)
	v_cvt_pk_f32_fp8_e32 v[88:89], v106
	v_cvt_pk_f32_fp8_sdwa v[90:91], v106 src0_sel:WORD_1
	v_mul_f32_e32 v120, v120, v126
	v_mul_f32_e32 v92, v92, v120
	v_mul_f32_e32 v106, 0xbfb8aa3b, v88
	v_exp_f32_e32 v120, v106
	v_mul_f32_e32 v127, 0xbfb8aa3b, v121
	v_mov_b32_e32 v108, v116
	v_mov_b32_e32 v109, v117
	v_exp_f32_e32 v127, v127
	v_add_f32_e32 v116, 1.0, v120
	v_rcp_f32_e32 v116, v116
	v_mul_f32_e32 v117, 0xbfb8aa3b, v89
	v_exp_f32_e32 v117, v117
	v_mul_f32_e32 v135, 0xbfb8aa3b, v122
	v_mul_f32_e32 v142, 0xbfb8aa3b, v123
	v_exp_f32_e32 v135, v135
	v_exp_f32_e32 v142, v142
	v_add_f32_e32 v127, 1.0, v127
	v_mul_f32_e32 v88, v88, v116
	v_rcp_f32_e32 v127, v127
	v_mul_f32_e32 v108, v108, v88
	v_add_f32_e32 v88, 1.0, v117
	v_mul_f32_e32 v116, 0xbfb8aa3b, v90
	v_rcp_f32_e32 v88, v88
	v_exp_f32_e32 v116, v116
	v_mul_f32_e32 v117, 0xbfb8aa3b, v91
	v_exp_f32_e32 v117, v117
	v_add_f32_e32 v135, 1.0, v135
	v_add_f32_e32 v142, 1.0, v142
	v_rcp_f32_e32 v135, v135
	v_rcp_f32_e32 v142, v142
	v_mul_f32_e32 v121, v121, v127
	v_mul_f32_e32 v93, v93, v121
	v_mul_f32_e32 v88, v89, v88
	v_add_f32_e32 v89, 1.0, v116
	v_cvt_scalef32_pk_fp8_f32 v110, v92, v93, s12
	v_cvt_pk_f32_fp8_e32 v[92:93], v107
	v_rcp_f32_e32 v89, v89
	v_add_f32_e32 v116, 1.0, v117
	v_rcp_f32_e32 v116, v116
	v_mul_f32_e32 v122, v122, v135
	v_mul_f32_e32 v123, v123, v142
	v_mul_f32_e32 v94, v94, v122
	v_mul_f32_e32 v95, v95, v123
	v_cvt_scalef32_pk_fp8_f32 v110, v94, v95, s12 op_sel:[0,0,0,1]
	v_cvt_pk_f32_fp8_sdwa v[94:95], v107 src0_sel:WORD_1
	v_mov_b32_e32 v106, v118
	v_mov_b32_e32 v107, v119
	v_mul_f32_e32 v109, v109, v88
	v_mul_f32_e32 v88, v90, v89
	v_mul_f32_e32 v89, 0xbfb8aa3b, v92
	v_mul_f32_e32 v90, v106, v88
	v_mul_f32_e32 v88, v91, v116
	v_exp_f32_e32 v89, v89
	v_mul_f32_e32 v91, 0xbfb8aa3b, v93
	v_exp_f32_e32 v91, v91
	v_mul_f32_e32 v106, v107, v88
	v_add_f32_e32 v88, 1.0, v89
	v_rcp_f32_e32 v88, v88
	v_add_f32_e32 v89, 1.0, v91
	v_mul_f32_e32 v91, 0xbfb8aa3b, v94
	v_rcp_f32_e32 v89, v89
	v_exp_f32_e32 v91, v91
	v_mul_f32_e32 v88, v92, v88
	v_mul_f32_e32 v92, v112, v88
	v_mul_f32_e32 v88, v93, v89
	v_add_f32_e32 v89, 1.0, v91
	v_rcp_f32_e32 v89, v89
	v_mul_f32_e32 v91, 0xbfb8aa3b, v95
	v_exp_f32_e32 v91, v91
	v_mul_f32_e32 v93, v113, v88
	v_mul_f32_e32 v88, v94, v89
	v_mul_f32_e32 v94, v114, v88
	v_add_f32_e32 v88, 1.0, v91
	v_rcp_f32_e32 v91, v88
	v_mov_b32_e32 v88, 0
	v_mov_b32_e32 v89, 0
	v_cvt_scalef32_pk_fp8_f32 v88, v108, v109, s12
	v_cvt_scalef32_pk_fp8_f32 v89, v92, v93, s12
	v_mul_f32_e32 v91, v95, v91
	v_mul_f32_e32 v91, v115, v91
	v_cvt_scalef32_pk_fp8_f32 v88, v90, v106, s12 op_sel:[0,0,0,1]
	v_cvt_scalef32_pk_fp8_f32 v89, v94, v91, s12 op_sel:[0,0,0,1]
	v_lshl_add_u64 v[90:91], s[38:39], 0, v[104:105]
	global_store_dwordx2 v[90:91], v[110:111], off
	global_store_dwordx2 v[90:91], v[88:89], off offset:128
	v_or_b32_e32 v88, 32, v134
	v_ashrrev_i32_e32 v89, 31, v88
	v_lshlrev_b64 v[88:89], 12, v[88:89]
	v_lshl_add_u64 v[88:89], v[88:89], 0, v[136:137]
	v_lshl_add_u64 v[90:91], s[30:31], 0, v[88:89]
	global_load_dwordx2 v[92:93], v[90:91], off
	s_nop 0
	global_load_dwordx2 v[90:91], v[90:91], off offset:128
	s_waitcnt vmcnt(1)
	v_cvt_pk_f32_fp8_e32 v[94:95], v92
	v_cvt_pk_f32_fp8_sdwa v[104:105], v92 src0_sel:WORD_1
	v_cvt_pk_f32_fp8_e32 v[106:107], v93
	v_cvt_pk_f32_fp8_sdwa v[92:93], v93 src0_sel:WORD_1
	v_mul_f32_e32 v109, 0xbfb8aa3b, v95
	v_mul_f32_e32 v108, 0xbfb8aa3b, v94
	v_exp_f32_e32 v109, v109
	v_mul_f32_e32 v110, 0xbfb8aa3b, v104
	v_exp_f32_e32 v108, v108
	v_exp_f32_e32 v110, v110
	v_mul_f32_e32 v111, 0xbfb8aa3b, v105
	v_add_f32_e32 v109, 1.0, v109
	v_exp_f32_e32 v111, v111
	v_add_f32_e32 v108, 1.0, v108
	v_rcp_f32_e32 v109, v109
	v_add_f32_e32 v110, 1.0, v110
	v_rcp_f32_e32 v108, v108
	v_rcp_f32_e32 v110, v110
	v_add_f32_e32 v111, 1.0, v111
	v_mul_f32_e32 v95, v95, v109
	v_rcp_f32_e32 v111, v111
	v_mul_f32_e32 v94, v94, v108
	v_mul_f32_e32 v77, v77, v95
	v_mul_f32_e32 v95, 0xbfb8aa3b, v106
	v_mul_f32_e32 v76, v76, v94
	v_mul_f32_e32 v94, v104, v110
	v_exp_f32_e32 v95, v95
	v_mul_f32_e32 v104, 0xbfb8aa3b, v107
	v_exp_f32_e32 v104, v104
	v_mul_f32_e32 v78, v78, v94
	v_mul_f32_e32 v94, v105, v111
	v_mul_f32_e32 v79, v79, v94
	v_add_f32_e32 v94, 1.0, v95
	v_rcp_f32_e32 v94, v94
	v_add_f32_e32 v95, 1.0, v104
	v_mul_f32_e32 v104, 0xbfb8aa3b, v92
	v_rcp_f32_e32 v95, v95
	v_exp_f32_e32 v104, v104
	v_mul_f32_e32 v94, v106, v94
	v_mul_f32_e32 v94, v72, v94
	v_mul_f32_e32 v72, v107, v95
	v_add_f32_e32 v95, 1.0, v104
	v_rcp_f32_e32 v95, v95
	v_mul_f32_e32 v104, 0xbfb8aa3b, v93
	v_exp_f32_e32 v104, v104
	v_mul_f32_e32 v105, v73, v72
	v_mul_f32_e32 v72, v92, v95
	v_mul_f32_e32 v74, v74, v72
	v_add_f32_e32 v72, 1.0, v104
	v_rcp_f32_e32 v92, v72
	v_mov_b32_e32 v73, 0
	v_cvt_scalef32_pk_fp8_f32 v73, v94, v105, s12
	v_mov_b32_e32 v72, 0
	v_cvt_scalef32_pk_fp8_f32 v72, v76, v77, s12
	v_mul_f32_e32 v76, v93, v92
	v_mul_f32_e32 v75, v75, v76
	v_cvt_scalef32_pk_fp8_f32 v73, v74, v75, s12 op_sel:[0,0,0,1]
	s_waitcnt vmcnt(0)
; __device__ __forceinline__ float silu_fast(float z) { return z * __builtin_amdgcn_rcpf(1.f + __builtin_amdgcn_exp2f(-1.4426950408889634f * z)); }
;   __device__ __forceinline__ void operator()(const Acc& acc, const GUnit& u, int wr, int wc, int fr, int fq) const {
;     ...
;       for (int m = 0; m < 4; ++m) {
;         const size_t off = (size_t)(row0 + ai * 128 + m * 16) * 4096 + col0;
; #pragma unroll
;         for (int bj = 0; bj < 2; ++bj) {
;           const u32x2 zw = *(const u32x2*)(Z + off + bj * 128);
;           typedef float f32x2v __attribute__((ext_vector_type(2)));
;           const f32x2v z0 = __builtin_amdgcn_cvt_pk_f32_fp8(zw[0], false), z1 = __builtin_amdgcn_cvt_pk_f32_fp8(zw[0], true), z2 = __builtin_amdgcn_cvt_pk_f32_fp8(zw[1], false), z3 = __builtin_amdgcn_cvt_pk_f32_fp8(zw[1], true);
;           f32x4 a = acc[ai][bj][m][0] * osc, b = acc[ai][bj][m][1] * osc;
;           a[0] *= silu_fast(z0[0]); a[1] *= silu_fast(z0[1]); a[2] *= silu_fast(z1[0]); a[3] *= silu_fast(z1[1]);
;           b[0] *= silu_fast(z2[0]); b[1] *= silu_fast(z2[1]); b[2] *= silu_fast(z3[0]); b[3] *= silu_fast(z3[1]);
;           u32x2 w; w[0] = __builtin_amdgcn_cvt_pk_fp8_f32(a[0], a[1], 0, false); w[0] = __builtin_amdgcn_cvt_pk_fp8_f32(a[2], a[3], w[0], true);
;           w[1] = __builtin_amdgcn_cvt_pk_fp8_f32(b[0], b[1], 0, false); w[1] = __builtin_amdgcn_cvt_pk_fp8_f32(b[2], b[3], w[1], true);
;           *(u32x2*)(Y + off + bj * 128) = w;
;         }
	v_cvt_pk_f32_fp8_e32 v[74:75], v90
	v_mov_b32_e32 v94, v100
	v_mov_b32_e32 v95, v101
	v_cvt_pk_f32_fp8_sdwa v[76:77], v90 src0_sel:WORD_1
	v_cvt_scalef32_pk_fp8_f32 v72, v78, v79, s12 op_sel:[0,0,0,1]
	v_mul_f32_e32 v92, 0xbfb8aa3b, v74
	v_exp_f32_e32 v104, v92
	v_mul_f32_e32 v101, 0xbfb8aa3b, v75
	v_exp_f32_e32 v101, v101
	v_cvt_pk_f32_fp8_e32 v[78:79], v91
	v_add_f32_e32 v100, 1.0, v104
	v_rcp_f32_e32 v100, v100
	v_mov_b32_e32 v92, v102
	v_mov_b32_e32 v93, v103
	v_cvt_pk_f32_fp8_sdwa v[90:91], v91 src0_sel:WORD_1
	v_mul_f32_e32 v74, v74, v100
	v_mul_f32_e32 v94, v94, v74
	v_add_f32_e32 v74, 1.0, v101
	v_mul_f32_e32 v100, 0xbfb8aa3b, v76
	v_rcp_f32_e32 v74, v74
	v_exp_f32_e32 v100, v100
	v_mul_f32_e32 v101, 0xbfb8aa3b, v77
	v_exp_f32_e32 v101, v101
	v_mul_f32_e32 v74, v75, v74
	v_add_f32_e32 v75, 1.0, v100
	v_rcp_f32_e32 v75, v75
	v_add_f32_e32 v100, 1.0, v101
	v_rcp_f32_e32 v100, v100
	v_mul_f32_e32 v95, v95, v74
	v_mul_f32_e32 v74, v76, v75
	v_mul_f32_e32 v75, 0xbfb8aa3b, v78
	v_mul_f32_e32 v76, v92, v74
	v_mul_f32_e32 v74, v77, v100
	v_exp_f32_e32 v75, v75
	v_mul_f32_e32 v77, 0xbfb8aa3b, v79
	v_exp_f32_e32 v77, v77
	v_mul_f32_e32 v92, v93, v74
	v_add_f32_e32 v74, 1.0, v75
	v_rcp_f32_e32 v74, v74
	v_add_f32_e32 v75, 1.0, v77
	v_mul_f32_e32 v77, 0xbfb8aa3b, v90
	v_rcp_f32_e32 v75, v75
	v_exp_f32_e32 v77, v77
	v_mul_f32_e32 v74, v78, v74
	v_mul_f32_e32 v78, v96, v74
	v_mul_f32_e32 v74, v79, v75
	v_add_f32_e32 v75, 1.0, v77
	v_rcp_f32_e32 v75, v75
	v_mul_f32_e32 v77, 0xbfb8aa3b, v91
	v_exp_f32_e32 v77, v77
	v_mul_f32_e32 v79, v97, v74
	v_mul_f32_e32 v74, v90, v75
	v_mul_f32_e32 v90, v98, v74
	v_add_f32_e32 v74, 1.0, v77
	v_rcp_f32_e32 v77, v74
	v_mov_b32_e32 v74, 0
	v_mov_b32_e32 v75, 0
	v_cvt_scalef32_pk_fp8_f32 v74, v94, v95, s12
	v_cvt_scalef32_pk_fp8_f32 v75, v78, v79, s12
	v_mul_f32_e32 v77, v91, v77
	v_mul_f32_e32 v77, v99, v77
	v_cvt_scalef32_pk_fp8_f32 v74, v76, v92, s12 op_sel:[0,0,0,1]
	v_cvt_scalef32_pk_fp8_f32 v75, v90, v77, s12 op_sel:[0,0,0,1]
	v_lshl_add_u64 v[76:77], s[38:39], 0, v[88:89]
	global_store_dwordx2 v[76:77], v[72:73], off
	global_store_dwordx2 v[76:77], v[74:75], off offset:128
	v_or_b32_e32 v72, 48, v134
	v_ashrrev_i32_e32 v73, 31, v72
	v_lshlrev_b64 v[72:73], 12, v[72:73]
	v_lshl_add_u64 v[72:73], v[72:73], 0, v[136:137]
	v_lshl_add_u64 v[74:75], s[30:31], 0, v[72:73]
	global_load_dwordx2 v[76:77], v[74:75], off
	s_nop 0
	global_load_dwordx2 v[74:75], v[74:75], off offset:128
	s_waitcnt vmcnt(1)
	v_cvt_pk_f32_fp8_e32 v[78:79], v76
	v_cvt_pk_f32_fp8_sdwa v[88:89], v76 src0_sel:WORD_1
	v_cvt_pk_f32_fp8_e32 v[90:91], v77
	v_cvt_pk_f32_fp8_sdwa v[76:77], v77 src0_sel:WORD_1
	v_mul_f32_e32 v92, 0xbfb8aa3b, v78
	v_exp_f32_e32 v92, v92
	v_mul_f32_e32 v93, 0xbfb8aa3b, v79
	v_exp_f32_e32 v93, v93
	v_add_f32_e32 v92, 1.0, v92
	v_rcp_f32_e32 v92, v92
	s_nop 0
	v_mul_f32_e32 v78, v78, v92
	v_mul_f32_e32 v60, v60, v78
	v_add_f32_e32 v78, 1.0, v93
	v_mul_f32_e32 v92, 0xbfb8aa3b, v88
	v_rcp_f32_e32 v78, v78
	v_exp_f32_e32 v92, v92
	v_mul_f32_e32 v93, 0xbfb8aa3b, v89
	v_exp_f32_e32 v93, v93
	v_mul_f32_e32 v78, v79, v78
	v_add_f32_e32 v79, 1.0, v92
	v_rcp_f32_e32 v79, v79
	v_add_f32_e32 v92, 1.0, v93
	v_rcp_f32_e32 v92, v92
	v_mul_f32_e32 v61, v61, v78
	v_mul_f32_e32 v78, v88, v79
	v_mul_f32_e32 v79, 0xbfb8aa3b, v90
	v_exp_f32_e32 v79, v79
	v_mul_f32_e32 v88, 0xbfb8aa3b, v91
	v_exp_f32_e32 v88, v88
	v_mul_f32_e32 v62, v62, v78
	v_mul_f32_e32 v78, v89, v92
	v_mul_f32_e32 v63, v63, v78
	v_add_f32_e32 v78, 1.0, v79
	v_rcp_f32_e32 v78, v78
	v_add_f32_e32 v79, 1.0, v88
	v_mul_f32_e32 v88, 0xbfb8aa3b, v76
	v_rcp_f32_e32 v79, v79
	v_exp_f32_e32 v88, v88
	v_mul_f32_e32 v78, v90, v78
	v_mul_f32_e32 v78, v56, v78
	v_mul_f32_e32 v56, v91, v79
	v_add_f32_e32 v79, 1.0, v88
	v_rcp_f32_e32 v79, v79
	v_mul_f32_e32 v88, 0xbfb8aa3b, v77
	v_exp_f32_e32 v88, v88
	v_mul_f32_e32 v89, v57, v56
	v_mul_f32_e32 v56, v76, v79
	v_mul_f32_e32 v58, v58, v56
	v_add_f32_e32 v56, 1.0, v88
	v_rcp_f32_e32 v76, v56
	v_mov_b32_e32 v57, 0
	v_cvt_scalef32_pk_fp8_f32 v57, v78, v89, s12
	v_mov_b32_e32 v56, 0
	v_cvt_scalef32_pk_fp8_f32 v56, v60, v61, s12
	v_mul_f32_e32 v60, v77, v76
	v_mul_f32_e32 v59, v59, v60
	v_cvt_scalef32_pk_fp8_f32 v57, v58, v59, s12 op_sel:[0,0,0,1]
	s_waitcnt vmcnt(0)
	v_cvt_pk_f32_fp8_e32 v[58:59], v74
	v_mov_b32_e32 v78, v84
	v_mov_b32_e32 v79, v85
	v_cvt_pk_f32_fp8_sdwa v[60:61], v74 src0_sel:WORD_1
	v_cvt_scalef32_pk_fp8_f32 v56, v62, v63, s12 op_sel:[0,0,0,1]
	v_mul_f32_e32 v76, 0xbfb8aa3b, v58
	v_exp_f32_e32 v88, v76
	v_mul_f32_e32 v85, 0xbfb8aa3b, v59
	v_exp_f32_e32 v85, v85
	v_cvt_pk_f32_fp8_e32 v[62:63], v75
	v_add_f32_e32 v84, 1.0, v88
	v_rcp_f32_e32 v84, v84
	v_mov_b32_e32 v76, v86
	v_mov_b32_e32 v77, v87
	v_cvt_pk_f32_fp8_sdwa v[74:75], v75 src0_sel:WORD_1
	v_mul_f32_e32 v58, v58, v84
	v_mul_f32_e32 v78, v78, v58
	v_add_f32_e32 v58, 1.0, v85
	v_mul_f32_e32 v84, 0xbfb8aa3b, v60
	v_rcp_f32_e32 v58, v58
	v_exp_f32_e32 v84, v84
	v_mul_f32_e32 v85, 0xbfb8aa3b, v61
	v_exp_f32_e32 v85, v85
	v_mul_f32_e32 v58, v59, v58
	v_add_f32_e32 v59, 1.0, v84
	v_rcp_f32_e32 v59, v59
	v_add_f32_e32 v84, 1.0, v85
	v_rcp_f32_e32 v84, v84
	v_mul_f32_e32 v79, v79, v58
	v_mul_f32_e32 v58, v60, v59
	v_mul_f32_e32 v59, 0xbfb8aa3b, v62
	v_mul_f32_e32 v60, v76, v58
	v_mul_f32_e32 v58, v61, v84
	v_exp_f32_e32 v59, v59
	v_mul_f32_e32 v61, 0xbfb8aa3b, v63
	v_exp_f32_e32 v61, v61
	v_mul_f32_e32 v76, v77, v58
	v_add_f32_e32 v58, 1.0, v59
	v_rcp_f32_e32 v58, v58
	v_add_f32_e32 v59, 1.0, v61
	v_mul_f32_e32 v61, 0xbfb8aa3b, v74
	v_rcp_f32_e32 v59, v59
	v_exp_f32_e32 v61, v61
	v_mul_f32_e32 v58, v62, v58
	v_mul_f32_e32 v62, v80, v58
	v_mul_f32_e32 v58, v63, v59
	v_add_f32_e32 v59, 1.0, v61
	v_rcp_f32_e32 v59, v59
	v_mul_f32_e32 v61, 0xbfb8aa3b, v75
	v_exp_f32_e32 v61, v61
	v_mul_f32_e32 v63, v81, v58
	v_mul_f32_e32 v58, v74, v59
	v_mul_f32_e32 v74, v82, v58
	v_add_f32_e32 v58, 1.0, v61
	v_rcp_f32_e32 v61, v58
	v_mov_b32_e32 v58, 0
	v_mov_b32_e32 v59, 0
	v_cvt_scalef32_pk_fp8_f32 v58, v78, v79, s12
	v_cvt_scalef32_pk_fp8_f32 v59, v62, v63, s12
	v_mul_f32_e32 v61, v75, v61
	v_mul_f32_e32 v61, v83, v61
	v_cvt_scalef32_pk_fp8_f32 v58, v60, v76, s12 op_sel:[0,0,0,1]
	v_cvt_scalef32_pk_fp8_f32 v59, v74, v61, s12 op_sel:[0,0,0,1]
	v_lshl_add_u64 v[60:61], s[38:39], 0, v[72:73]
	global_store_dwordx2 v[60:61], v[56:57], off
	global_store_dwordx2 v[60:61], v[58:59], off offset:128
	v_lshl_add_u64 v[56:57], v[132:133], 0, s[8:9]
	v_lshl_add_u64 v[58:59], s[30:31], 0, v[56:57]
	global_load_dwordx2 v[60:61], v[58:59], off
	s_nop 0
	global_load_dwordx2 v[58:59], v[58:59], off offset:128
	s_waitcnt vmcnt(1)
; __device__ __forceinline__ float silu_fast(float z) { return z * __builtin_amdgcn_rcpf(1.f + __builtin_amdgcn_exp2f(-1.4426950408889634f * z)); }
;   __device__ __forceinline__ void operator()(const Acc& acc, const GUnit& u, int wr, int wc, int fr, int fq) const {
;     ...
;       for (int m = 0; m < 4; ++m) {
;         const size_t off = (size_t)(row0 + ai * 128 + m * 16) * 4096 + col0;
; #pragma unroll
;         for (int bj = 0; bj < 2; ++bj) {
;           const u32x2 zw = *(const u32x2*)(Z + off + bj * 128);
;           typedef float f32x2v __attribute__((ext_vector_type(2)));
;           const f32x2v z0 = __builtin_amdgcn_cvt_pk_f32_fp8(zw[0], false), z1 = __builtin_amdgcn_cvt_pk_f32_fp8(zw[0], true), z2 = __builtin_amdgcn_cvt_pk_f32_fp8(zw[1], false), z3 = __builtin_amdgcn_cvt_pk_f32_fp8(zw[1], true);
;           f32x4 a = acc[ai][bj][m][0] * osc, b = acc[ai][bj][m][1] * osc;
;           a[0] *= silu_fast(z0[0]); a[1] *= silu_fast(z0[1]); a[2] *= silu_fast(z1[0]); a[3] *= silu_fast(z1[1]);
;           b[0] *= silu_fast(z2[0]); b[1] *= silu_fast(z2[1]); b[2] *= silu_fast(z3[0]); b[3] *= silu_fast(z3[1]);
;           u32x2 w; w[0] = __builtin_amdgcn_cvt_pk_fp8_f32(a[0], a[1], 0, false); w[0] = __builtin_amdgcn_cvt_pk_fp8_f32(a[2], a[3], w[0], true);
;           w[1] = __builtin_amdgcn_cvt_pk_fp8_f32(b[0], b[1], 0, false); w[1] = __builtin_amdgcn_cvt_pk_fp8_f32(b[2], b[3], w[1], true);
;           *(u32x2*)(Y + off + bj * 128) = w;
;         }
	v_cvt_pk_f32_fp8_e32 v[62:63], v60
	v_cvt_pk_f32_fp8_sdwa v[72:73], v60 src0_sel:WORD_1
	v_cvt_pk_f32_fp8_e32 v[74:75], v61
	v_cvt_pk_f32_fp8_sdwa v[60:61], v61 src0_sel:WORD_1
	v_mul_f32_e32 v76, 0xbfb8aa3b, v62
	v_exp_f32_e32 v76, v76
	v_mul_f32_e32 v77, 0xbfb8aa3b, v63
	v_exp_f32_e32 v77, v77
	v_add_f32_e32 v76, 1.0, v76
	v_rcp_f32_e32 v76, v76
	s_nop 0
	v_mul_f32_e32 v62, v62, v76
	v_mul_f32_e32 v44, v44, v62
	v_add_f32_e32 v62, 1.0, v77
	v_mul_f32_e32 v76, 0xbfb8aa3b, v72
	v_rcp_f32_e32 v62, v62
	v_exp_f32_e32 v76, v76
	v_mul_f32_e32 v77, 0xbfb8aa3b, v73
	v_exp_f32_e32 v77, v77
	v_mul_f32_e32 v62, v63, v62
	v_add_f32_e32 v63, 1.0, v76
	v_rcp_f32_e32 v63, v63
	v_add_f32_e32 v76, 1.0, v77
	v_rcp_f32_e32 v76, v76
	v_mul_f32_e32 v45, v45, v62
	v_mul_f32_e32 v62, v72, v63
	v_mul_f32_e32 v63, 0xbfb8aa3b, v74
	v_exp_f32_e32 v63, v63
	v_mul_f32_e32 v72, 0xbfb8aa3b, v75
	v_exp_f32_e32 v72, v72
	v_mul_f32_e32 v46, v46, v62
	v_mul_f32_e32 v62, v73, v76
	v_mul_f32_e32 v47, v47, v62
	v_add_f32_e32 v62, 1.0, v63
	v_rcp_f32_e32 v62, v62
	v_add_f32_e32 v63, 1.0, v72
	v_mul_f32_e32 v72, 0xbfb8aa3b, v60
	v_rcp_f32_e32 v63, v63
	v_exp_f32_e32 v72, v72
	v_mul_f32_e32 v62, v74, v62
	v_mul_f32_e32 v62, v40, v62
	v_mul_f32_e32 v40, v75, v63
	v_add_f32_e32 v63, 1.0, v72
	v_rcp_f32_e32 v63, v63
	v_mul_f32_e32 v72, 0xbfb8aa3b, v61
	v_exp_f32_e32 v72, v72
	v_mul_f32_e32 v73, v41, v40
	v_mul_f32_e32 v40, v60, v63
	v_mul_f32_e32 v42, v42, v40
	v_add_f32_e32 v40, 1.0, v72
	v_rcp_f32_e32 v60, v40
	v_mov_b32_e32 v41, 0
	v_cvt_scalef32_pk_fp8_f32 v41, v62, v73, s12
	v_mov_b32_e32 v40, 0
	v_cvt_scalef32_pk_fp8_f32 v40, v44, v45, s12
	v_mul_f32_e32 v44, v61, v60
	v_mul_f32_e32 v43, v43, v44
	v_cvt_scalef32_pk_fp8_f32 v41, v42, v43, s12 op_sel:[0,0,0,1]
	s_waitcnt vmcnt(0)
	v_cvt_pk_f32_fp8_e32 v[42:43], v58
	v_mov_b32_e32 v62, v68
	v_mov_b32_e32 v63, v69
	v_cvt_pk_f32_fp8_sdwa v[44:45], v58 src0_sel:WORD_1
	v_cvt_scalef32_pk_fp8_f32 v40, v46, v47, s12 op_sel:[0,0,0,1]
	v_mul_f32_e32 v60, 0xbfb8aa3b, v42
	v_exp_f32_e32 v72, v60
	v_mul_f32_e32 v69, 0xbfb8aa3b, v43
	v_exp_f32_e32 v69, v69
	v_cvt_pk_f32_fp8_e32 v[46:47], v59
	v_add_f32_e32 v68, 1.0, v72
	v_rcp_f32_e32 v68, v68
	v_mov_b32_e32 v60, v70
	v_mov_b32_e32 v61, v71
	v_cvt_pk_f32_fp8_sdwa v[58:59], v59 src0_sel:WORD_1
	v_mul_f32_e32 v42, v42, v68
	v_mul_f32_e32 v62, v62, v42
	v_add_f32_e32 v42, 1.0, v69
	v_mul_f32_e32 v68, 0xbfb8aa3b, v44
	v_rcp_f32_e32 v42, v42
	v_exp_f32_e32 v68, v68
	v_mul_f32_e32 v69, 0xbfb8aa3b, v45
	v_exp_f32_e32 v69, v69
	v_mul_f32_e32 v42, v43, v42
	v_add_f32_e32 v43, 1.0, v68
	v_rcp_f32_e32 v43, v43
	v_add_f32_e32 v68, 1.0, v69
	v_rcp_f32_e32 v68, v68
	v_mul_f32_e32 v63, v63, v42
	v_mul_f32_e32 v42, v44, v43
	v_mul_f32_e32 v43, 0xbfb8aa3b, v46
	v_mul_f32_e32 v44, v60, v42
	v_mul_f32_e32 v42, v45, v68
	v_exp_f32_e32 v43, v43
	v_mul_f32_e32 v45, 0xbfb8aa3b, v47
	v_exp_f32_e32 v45, v45
	v_mul_f32_e32 v60, v61, v42
	v_add_f32_e32 v42, 1.0, v43
	v_rcp_f32_e32 v42, v42
	v_add_f32_e32 v43, 1.0, v45
	v_mul_f32_e32 v45, 0xbfb8aa3b, v58
	v_rcp_f32_e32 v43, v43
	v_exp_f32_e32 v45, v45
	v_mul_f32_e32 v42, v46, v42
	v_mul_f32_e32 v46, v64, v42
	v_mul_f32_e32 v42, v47, v43
	v_add_f32_e32 v43, 1.0, v45
	v_rcp_f32_e32 v43, v43
	v_mul_f32_e32 v45, 0xbfb8aa3b, v59
	v_exp_f32_e32 v45, v45
	v_mul_f32_e32 v47, v65, v42
	v_mul_f32_e32 v42, v58, v43
	v_mul_f32_e32 v58, v66, v42
	v_add_f32_e32 v42, 1.0, v45
	v_rcp_f32_e32 v45, v42
	v_mov_b32_e32 v42, 0
	v_mov_b32_e32 v43, 0
	v_cvt_scalef32_pk_fp8_f32 v42, v62, v63, s12
	v_cvt_scalef32_pk_fp8_f32 v43, v46, v47, s12
	v_mul_f32_e32 v45, v59, v45
	v_mul_f32_e32 v45, v67, v45
	v_cvt_scalef32_pk_fp8_f32 v42, v44, v60, s12 op_sel:[0,0,0,1]
	v_cvt_scalef32_pk_fp8_f32 v43, v58, v45, s12 op_sel:[0,0,0,1]
	v_lshl_add_u64 v[44:45], s[38:39], 0, v[56:57]
	global_store_dwordx2 v[44:45], v[40:41], off
	global_store_dwordx2 v[44:45], v[42:43], off offset:128
	v_lshl_add_u64 v[40:41], v[132:133], 0, s[14:15]
	v_lshl_add_u64 v[42:43], s[30:31], 0, v[40:41]
	global_load_dwordx2 v[44:45], v[42:43], off
	s_nop 0
	global_load_dwordx2 v[42:43], v[42:43], off offset:128
	s_waitcnt vmcnt(1)
	v_cvt_pk_f32_fp8_e32 v[46:47], v44
	v_cvt_pk_f32_fp8_sdwa v[56:57], v44 src0_sel:WORD_1
	v_cvt_pk_f32_fp8_e32 v[58:59], v45
	v_cvt_pk_f32_fp8_sdwa v[44:45], v45 src0_sel:WORD_1
	v_mul_f32_e32 v60, 0xbfb8aa3b, v46
	v_exp_f32_e32 v60, v60
	v_mul_f32_e32 v61, 0xbfb8aa3b, v47
	v_exp_f32_e32 v61, v61
	v_add_f32_e32 v60, 1.0, v60
	v_rcp_f32_e32 v60, v60
	s_nop 0
	v_mul_f32_e32 v46, v46, v60
	v_mul_f32_e32 v28, v28, v46
	v_add_f32_e32 v46, 1.0, v61
	v_mul_f32_e32 v60, 0xbfb8aa3b, v56
	v_rcp_f32_e32 v46, v46
	v_exp_f32_e32 v60, v60
	v_mul_f32_e32 v61, 0xbfb8aa3b, v57
	v_exp_f32_e32 v61, v61
	v_mul_f32_e32 v46, v47, v46
	v_add_f32_e32 v47, 1.0, v60
	v_rcp_f32_e32 v47, v47
	v_add_f32_e32 v60, 1.0, v61
	v_rcp_f32_e32 v60, v60
	v_mul_f32_e32 v29, v29, v46
	v_mul_f32_e32 v46, v56, v47
	v_mul_f32_e32 v47, 0xbfb8aa3b, v58
	v_exp_f32_e32 v47, v47
	v_mul_f32_e32 v56, 0xbfb8aa3b, v59
	v_exp_f32_e32 v56, v56
	v_mul_f32_e32 v30, v30, v46
	v_mul_f32_e32 v46, v57, v60
	v_mul_f32_e32 v31, v31, v46
	v_add_f32_e32 v46, 1.0, v47
	v_rcp_f32_e32 v46, v46
	v_add_f32_e32 v47, 1.0, v56
	v_mul_f32_e32 v56, 0xbfb8aa3b, v44
	v_rcp_f32_e32 v47, v47
	v_exp_f32_e32 v56, v56
	v_mul_f32_e32 v46, v58, v46
	v_mul_f32_e32 v46, v24, v46
	v_mul_f32_e32 v24, v59, v47
	v_add_f32_e32 v47, 1.0, v56
	v_rcp_f32_e32 v47, v47
	v_mul_f32_e32 v56, 0xbfb8aa3b, v45
	v_exp_f32_e32 v56, v56
	v_mul_f32_e32 v57, v25, v24
	v_mul_f32_e32 v24, v44, v47
	v_mul_f32_e32 v26, v26, v24
	v_add_f32_e32 v24, 1.0, v56
	v_rcp_f32_e32 v44, v24
	v_mov_b32_e32 v25, 0
	v_cvt_scalef32_pk_fp8_f32 v25, v46, v57, s12
	v_mov_b32_e32 v24, 0
	v_cvt_scalef32_pk_fp8_f32 v24, v28, v29, s12
	v_mul_f32_e32 v28, v45, v44
	v_mul_f32_e32 v27, v27, v28
	v_cvt_scalef32_pk_fp8_f32 v25, v26, v27, s12 op_sel:[0,0,0,1]
	s_waitcnt vmcnt(0)
; __device__ __forceinline__ float silu_fast(float z) { return z * __builtin_amdgcn_rcpf(1.f + __builtin_amdgcn_exp2f(-1.4426950408889634f * z)); }
;   __device__ __forceinline__ void operator()(const Acc& acc, const GUnit& u, int wr, int wc, int fr, int fq) const {
;     ...
;       for (int m = 0; m < 4; ++m) {
;         const size_t off = (size_t)(row0 + ai * 128 + m * 16) * 4096 + col0;
; #pragma unroll
;         for (int bj = 0; bj < 2; ++bj) {
;           const u32x2 zw = *(const u32x2*)(Z + off + bj * 128);
;           typedef float f32x2v __attribute__((ext_vector_type(2)));
;           const f32x2v z0 = __builtin_amdgcn_cvt_pk_f32_fp8(zw[0], false), z1 = __builtin_amdgcn_cvt_pk_f32_fp8(zw[0], true), z2 = __builtin_amdgcn_cvt_pk_f32_fp8(zw[1], false), z3 = __builtin_amdgcn_cvt_pk_f32_fp8(zw[1], true);
;           f32x4 a = acc[ai][bj][m][0] * osc, b = acc[ai][bj][m][1] * osc;
;           a[0] *= silu_fast(z0[0]); a[1] *= silu_fast(z0[1]); a[2] *= silu_fast(z1[0]); a[3] *= silu_fast(z1[1]);
;           b[0] *= silu_fast(z2[0]); b[1] *= silu_fast(z2[1]); b[2] *= silu_fast(z3[0]); b[3] *= silu_fast(z3[1]);
;           u32x2 w; w[0] = __builtin_amdgcn_cvt_pk_fp8_f32(a[0], a[1], 0, false); w[0] = __builtin_amdgcn_cvt_pk_fp8_f32(a[2], a[3], w[0], true);
;           w[1] = __builtin_amdgcn_cvt_pk_fp8_f32(b[0], b[1], 0, false); w[1] = __builtin_amdgcn_cvt_pk_fp8_f32(b[2], b[3], w[1], true);
;           *(u32x2*)(Y + off + bj * 128) = w;
;         }
	v_cvt_pk_f32_fp8_e32 v[26:27], v42
	v_mov_b32_e32 v46, v52
	v_mov_b32_e32 v47, v53
	v_cvt_pk_f32_fp8_sdwa v[28:29], v42 src0_sel:WORD_1
	v_cvt_scalef32_pk_fp8_f32 v24, v30, v31, s12 op_sel:[0,0,0,1]
	v_mul_f32_e32 v44, 0xbfb8aa3b, v26
	v_exp_f32_e32 v56, v44
	v_mul_f32_e32 v53, 0xbfb8aa3b, v27
	v_exp_f32_e32 v53, v53
	v_cvt_pk_f32_fp8_e32 v[30:31], v43
	v_add_f32_e32 v52, 1.0, v56
	v_rcp_f32_e32 v52, v52
	v_mov_b32_e32 v44, v54
	v_mov_b32_e32 v45, v55
	v_cvt_pk_f32_fp8_sdwa v[42:43], v43 src0_sel:WORD_1
	v_mul_f32_e32 v26, v26, v52
	v_mul_f32_e32 v46, v46, v26
	v_add_f32_e32 v26, 1.0, v53
	v_mul_f32_e32 v52, 0xbfb8aa3b, v28
	v_rcp_f32_e32 v26, v26
	v_exp_f32_e32 v52, v52
	v_mul_f32_e32 v53, 0xbfb8aa3b, v29
	v_exp_f32_e32 v53, v53
	v_mul_f32_e32 v26, v27, v26
	v_add_f32_e32 v27, 1.0, v52
	v_rcp_f32_e32 v27, v27
	v_add_f32_e32 v52, 1.0, v53
	v_rcp_f32_e32 v52, v52
	v_mul_f32_e32 v47, v47, v26
	v_mul_f32_e32 v26, v28, v27
	v_mul_f32_e32 v27, 0xbfb8aa3b, v30
	v_mul_f32_e32 v28, v44, v26
	v_mul_f32_e32 v26, v29, v52
	v_exp_f32_e32 v27, v27
	v_mul_f32_e32 v29, 0xbfb8aa3b, v31
	v_exp_f32_e32 v29, v29
	v_mul_f32_e32 v44, v45, v26
	v_add_f32_e32 v26, 1.0, v27
	v_rcp_f32_e32 v26, v26
	v_add_f32_e32 v27, 1.0, v29
	v_mul_f32_e32 v29, 0xbfb8aa3b, v42
	v_rcp_f32_e32 v27, v27
	v_exp_f32_e32 v29, v29
	v_mul_f32_e32 v26, v30, v26
	v_mul_f32_e32 v30, v48, v26
	v_mul_f32_e32 v26, v31, v27
	v_add_f32_e32 v27, 1.0, v29
	v_rcp_f32_e32 v27, v27
	v_mul_f32_e32 v29, 0xbfb8aa3b, v43
	v_exp_f32_e32 v29, v29
	v_mul_f32_e32 v31, v49, v26
	v_mul_f32_e32 v26, v42, v27
	v_mul_f32_e32 v42, v50, v26
	v_add_f32_e32 v26, 1.0, v29
	v_rcp_f32_e32 v29, v26
	v_mov_b32_e32 v26, 0
	v_mov_b32_e32 v27, 0
	v_cvt_scalef32_pk_fp8_f32 v26, v46, v47, s12
	v_cvt_scalef32_pk_fp8_f32 v27, v30, v31, s12
	v_mul_f32_e32 v29, v43, v29
	v_mul_f32_e32 v29, v51, v29
	v_cvt_scalef32_pk_fp8_f32 v26, v28, v44, s12 op_sel:[0,0,0,1]
	v_cvt_scalef32_pk_fp8_f32 v27, v42, v29, s12 op_sel:[0,0,0,1]
	v_lshl_add_u64 v[28:29], s[38:39], 0, v[40:41]
	global_store_dwordx2 v[28:29], v[24:25], off
	global_store_dwordx2 v[28:29], v[26:27], off offset:128
	v_lshl_add_u64 v[24:25], v[132:133], 0, s[16:17]
	v_lshl_add_u64 v[26:27], s[30:31], 0, v[24:25]
	global_load_dwordx2 v[28:29], v[26:27], off
	s_nop 0
	global_load_dwordx2 v[26:27], v[26:27], off offset:128
	s_waitcnt vmcnt(1)
	v_cvt_pk_f32_fp8_e32 v[30:31], v28
	v_cvt_pk_f32_fp8_sdwa v[40:41], v28 src0_sel:WORD_1
	v_cvt_pk_f32_fp8_e32 v[42:43], v29
	v_cvt_pk_f32_fp8_sdwa v[28:29], v29 src0_sel:WORD_1
	v_mul_f32_e32 v44, 0xbfb8aa3b, v30
	v_exp_f32_e32 v44, v44
	v_mul_f32_e32 v45, 0xbfb8aa3b, v31
	v_exp_f32_e32 v45, v45
	v_add_f32_e32 v44, 1.0, v44
	v_rcp_f32_e32 v44, v44
	s_nop 0
	v_mul_f32_e32 v30, v30, v44
	v_mul_f32_e32 v12, v12, v30
	v_add_f32_e32 v30, 1.0, v45
	v_mul_f32_e32 v44, 0xbfb8aa3b, v40
	v_rcp_f32_e32 v30, v30
	v_exp_f32_e32 v44, v44
	v_mul_f32_e32 v45, 0xbfb8aa3b, v41
	v_exp_f32_e32 v45, v45
	v_mul_f32_e32 v30, v31, v30
	v_add_f32_e32 v31, 1.0, v44
	v_rcp_f32_e32 v31, v31
	v_add_f32_e32 v44, 1.0, v45
	v_rcp_f32_e32 v44, v44
	v_mul_f32_e32 v13, v13, v30
	v_mul_f32_e32 v30, v40, v31
	v_mul_f32_e32 v31, 0xbfb8aa3b, v42
	v_exp_f32_e32 v31, v31
	v_mul_f32_e32 v40, 0xbfb8aa3b, v43
	v_exp_f32_e32 v40, v40
	v_mul_f32_e32 v14, v14, v30
	v_mul_f32_e32 v30, v41, v44
	v_mul_f32_e32 v15, v15, v30
	v_add_f32_e32 v30, 1.0, v31
	v_rcp_f32_e32 v30, v30
	v_add_f32_e32 v31, 1.0, v40
	v_mul_f32_e32 v40, 0xbfb8aa3b, v28
	v_rcp_f32_e32 v31, v31
	v_exp_f32_e32 v40, v40
	v_mul_f32_e32 v30, v42, v30
	v_mul_f32_e32 v30, v8, v30
	v_mul_f32_e32 v8, v43, v31
	v_add_f32_e32 v31, 1.0, v40
	v_rcp_f32_e32 v31, v31
	v_mul_f32_e32 v40, 0xbfb8aa3b, v29
	v_exp_f32_e32 v40, v40
	v_mul_f32_e32 v41, v9, v8
	v_mul_f32_e32 v8, v28, v31
	v_mul_f32_e32 v10, v10, v8
	v_add_f32_e32 v8, 1.0, v40
	v_rcp_f32_e32 v28, v8
	v_mov_b32_e32 v9, 0
	v_cvt_scalef32_pk_fp8_f32 v9, v30, v41, s12
	v_mov_b32_e32 v8, 0
	v_cvt_scalef32_pk_fp8_f32 v8, v12, v13, s12
	v_mul_f32_e32 v12, v29, v28
	v_mul_f32_e32 v11, v11, v12
	v_cvt_scalef32_pk_fp8_f32 v9, v10, v11, s12 op_sel:[0,0,0,1]
	s_waitcnt vmcnt(0)
; __device__ __forceinline__ float silu_fast(float z) { return z * __builtin_amdgcn_rcpf(1.f + __builtin_amdgcn_exp2f(-1.4426950408889634f * z)); }
;   __device__ __forceinline__ void operator()(const Acc& acc, const GUnit& u, int wr, int wc, int fr, int fq) const {
;     ...
;       for (int m = 0; m < 4; ++m) {
;         const size_t off = (size_t)(row0 + ai * 128 + m * 16) * 4096 + col0;
; #pragma unroll
;         for (int bj = 0; bj < 2; ++bj) {
;           const u32x2 zw = *(const u32x2*)(Z + off + bj * 128);
;           typedef float f32x2v __attribute__((ext_vector_type(2)));
;           const f32x2v z0 = __builtin_amdgcn_cvt_pk_f32_fp8(zw[0], false), z1 = __builtin_amdgcn_cvt_pk_f32_fp8(zw[0], true), z2 = __builtin_amdgcn_cvt_pk_f32_fp8(zw[1], false), z3 = __builtin_amdgcn_cvt_pk_f32_fp8(zw[1], true);
;           f32x4 a = acc[ai][bj][m][0] * osc, b = acc[ai][bj][m][1] * osc;
;           a[0] *= silu_fast(z0[0]); a[1] *= silu_fast(z0[1]); a[2] *= silu_fast(z1[0]); a[3] *= silu_fast(z1[1]);
;           b[0] *= silu_fast(z2[0]); b[1] *= silu_fast(z2[1]); b[2] *= silu_fast(z3[0]); b[3] *= silu_fast(z3[1]);
;           u32x2 w; w[0] = __builtin_amdgcn_cvt_pk_fp8_f32(a[0], a[1], 0, false); w[0] = __builtin_amdgcn_cvt_pk_fp8_f32(a[2], a[3], w[0], true);
;           w[1] = __builtin_amdgcn_cvt_pk_fp8_f32(b[0], b[1], 0, false); w[1] = __builtin_amdgcn_cvt_pk_fp8_f32(b[2], b[3], w[1], true);
;           *(u32x2*)(Y + off + bj * 128) = w;
;         }
	v_cvt_pk_f32_fp8_e32 v[10:11], v26
	v_mov_b32_e32 v30, v36
	v_mov_b32_e32 v31, v37
	v_cvt_pk_f32_fp8_sdwa v[12:13], v26 src0_sel:WORD_1
	v_cvt_scalef32_pk_fp8_f32 v8, v14, v15, s12 op_sel:[0,0,0,1]
	v_mul_f32_e32 v28, 0xbfb8aa3b, v10
	v_exp_f32_e32 v40, v28
	v_mul_f32_e32 v37, 0xbfb8aa3b, v11
	v_exp_f32_e32 v37, v37
	v_cvt_pk_f32_fp8_e32 v[14:15], v27
	v_add_f32_e32 v36, 1.0, v40
	v_rcp_f32_e32 v36, v36
	v_mov_b32_e32 v28, v38
	v_mov_b32_e32 v29, v39
	v_cvt_pk_f32_fp8_sdwa v[26:27], v27 src0_sel:WORD_1
	v_mul_f32_e32 v10, v10, v36
	v_mul_f32_e32 v30, v30, v10
	v_add_f32_e32 v10, 1.0, v37
	v_mul_f32_e32 v36, 0xbfb8aa3b, v12
	v_rcp_f32_e32 v10, v10
	v_exp_f32_e32 v36, v36
	v_mul_f32_e32 v37, 0xbfb8aa3b, v13
	v_exp_f32_e32 v37, v37
	v_mul_f32_e32 v10, v11, v10
	v_add_f32_e32 v11, 1.0, v36
	v_rcp_f32_e32 v11, v11
	v_add_f32_e32 v36, 1.0, v37
	v_rcp_f32_e32 v36, v36
	v_mul_f32_e32 v31, v31, v10
	v_mul_f32_e32 v10, v12, v11
	v_mul_f32_e32 v11, 0xbfb8aa3b, v14
	v_mul_f32_e32 v12, v28, v10
	v_mul_f32_e32 v10, v13, v36
	v_exp_f32_e32 v11, v11
	v_mul_f32_e32 v13, 0xbfb8aa3b, v15
	v_exp_f32_e32 v13, v13
	v_mul_f32_e32 v28, v29, v10
	v_add_f32_e32 v10, 1.0, v11
	v_rcp_f32_e32 v10, v10
	v_add_f32_e32 v11, 1.0, v13
	v_mul_f32_e32 v13, 0xbfb8aa3b, v26
	v_rcp_f32_e32 v11, v11
	v_exp_f32_e32 v13, v13
	v_mul_f32_e32 v10, v14, v10
	v_mul_f32_e32 v14, v32, v10
	v_mul_f32_e32 v10, v15, v11
	v_add_f32_e32 v11, 1.0, v13
	v_rcp_f32_e32 v11, v11
	v_mul_f32_e32 v13, 0xbfb8aa3b, v27
	v_exp_f32_e32 v13, v13
	v_mul_f32_e32 v15, v33, v10
	v_mul_f32_e32 v10, v26, v11
	v_mul_f32_e32 v26, v34, v10
	v_add_f32_e32 v10, 1.0, v13
	v_rcp_f32_e32 v13, v10
	v_mov_b32_e32 v10, 0
	v_mov_b32_e32 v11, 0
	v_cvt_scalef32_pk_fp8_f32 v10, v30, v31, s12
	v_cvt_scalef32_pk_fp8_f32 v11, v14, v15, s12
	v_mul_f32_e32 v13, v27, v13
	v_mul_f32_e32 v13, v35, v13
	v_cvt_scalef32_pk_fp8_f32 v10, v12, v28, s12 op_sel:[0,0,0,1]
	v_cvt_scalef32_pk_fp8_f32 v11, v26, v13, s12 op_sel:[0,0,0,1]
	v_lshl_add_u64 v[12:13], s[38:39], 0, v[24:25]
	global_store_dwordx2 v[12:13], v[8:9], off
	global_store_dwordx2 v[12:13], v[10:11], off offset:128
	v_lshl_add_u64 v[8:9], v[132:133], 0, s[18:19]
	v_lshl_add_u64 v[10:11], s[30:31], 0, v[8:9]
	global_load_dwordx2 v[12:13], v[10:11], off
	s_nop 0
	global_load_dwordx2 v[10:11], v[10:11], off offset:128
	s_waitcnt vmcnt(1)
	v_cvt_pk_f32_fp8_e32 v[14:15], v12
	v_cvt_pk_f32_fp8_sdwa v[24:25], v12 src0_sel:WORD_1
	v_cvt_pk_f32_fp8_e32 v[26:27], v13
	v_cvt_pk_f32_fp8_sdwa v[12:13], v13 src0_sel:WORD_1
	v_mul_f32_e32 v28, 0xbfb8aa3b, v14
	v_exp_f32_e32 v28, v28
	v_mul_f32_e32 v29, 0xbfb8aa3b, v15
	v_exp_f32_e32 v29, v29
	v_add_f32_e32 v28, 1.0, v28
	v_rcp_f32_e32 v28, v28
	s_nop 0
	v_mul_f32_e32 v14, v14, v28
	v_mul_f32_e32 v4, v4, v14
	v_add_f32_e32 v14, 1.0, v29
	v_mul_f32_e32 v28, 0xbfb8aa3b, v24
	v_rcp_f32_e32 v14, v14
	v_exp_f32_e32 v28, v28
	v_mul_f32_e32 v29, 0xbfb8aa3b, v25
	v_exp_f32_e32 v29, v29
	v_mul_f32_e32 v14, v15, v14
	v_add_f32_e32 v15, 1.0, v28
	v_rcp_f32_e32 v15, v15
	v_add_f32_e32 v28, 1.0, v29
	v_rcp_f32_e32 v28, v28
	v_mul_f32_e32 v5, v5, v14
	v_mul_f32_e32 v14, v24, v15
	v_mul_f32_e32 v15, 0xbfb8aa3b, v26
	v_exp_f32_e32 v15, v15
	v_mul_f32_e32 v24, 0xbfb8aa3b, v27
	v_exp_f32_e32 v24, v24
	v_mul_f32_e32 v6, v6, v14
	v_mul_f32_e32 v14, v25, v28
	v_mul_f32_e32 v7, v7, v14
	v_add_f32_e32 v14, 1.0, v15
	v_rcp_f32_e32 v14, v14
	v_add_f32_e32 v15, 1.0, v24
	v_mul_f32_e32 v24, 0xbfb8aa3b, v12
	v_rcp_f32_e32 v15, v15
	v_exp_f32_e32 v24, v24
	v_mul_f32_e32 v14, v26, v14
	v_mul_f32_e32 v14, v0, v14
	v_mul_f32_e32 v0, v27, v15
	v_add_f32_e32 v15, 1.0, v24
	v_rcp_f32_e32 v15, v15
	v_mul_f32_e32 v24, 0xbfb8aa3b, v13
	v_exp_f32_e32 v24, v24
	v_mul_f32_e32 v25, v1, v0
	v_mul_f32_e32 v0, v12, v15
	v_mul_f32_e32 v2, v2, v0
	v_add_f32_e32 v0, 1.0, v24
	v_rcp_f32_e32 v12, v0
	v_mov_b32_e32 v1, 0
	v_cvt_scalef32_pk_fp8_f32 v1, v14, v25, s12
	v_mov_b32_e32 v0, 0
	v_cvt_scalef32_pk_fp8_f32 v0, v4, v5, s12
	v_mul_f32_e32 v4, v13, v12
	v_mul_f32_e32 v3, v3, v4
	v_cvt_scalef32_pk_fp8_f32 v1, v2, v3, s12 op_sel:[0,0,0,1]
	s_waitcnt vmcnt(0)
	v_cvt_pk_f32_fp8_e32 v[2:3], v10
	v_mov_b32_e32 v14, v20
	v_mov_b32_e32 v15, v21
	v_cvt_pk_f32_fp8_sdwa v[4:5], v10 src0_sel:WORD_1
	v_cvt_scalef32_pk_fp8_f32 v0, v6, v7, s12 op_sel:[0,0,0,1]
	v_mul_f32_e32 v12, 0xbfb8aa3b, v2
	v_exp_f32_e32 v24, v12
	v_mul_f32_e32 v21, 0xbfb8aa3b, v3
	v_exp_f32_e32 v21, v21
	v_cvt_pk_f32_fp8_e32 v[6:7], v11
	v_add_f32_e32 v20, 1.0, v24
	v_rcp_f32_e32 v20, v20
	v_mov_b32_e32 v12, v22
	v_mov_b32_e32 v13, v23
	v_cvt_pk_f32_fp8_sdwa v[10:11], v11 src0_sel:WORD_1
	v_mul_f32_e32 v2, v2, v20
	v_mul_f32_e32 v14, v14, v2
	v_add_f32_e32 v2, 1.0, v21
	v_mul_f32_e32 v20, 0xbfb8aa3b, v4
	v_rcp_f32_e32 v2, v2
	v_exp_f32_e32 v20, v20
	v_mul_f32_e32 v21, 0xbfb8aa3b, v5
	v_exp_f32_e32 v21, v21
	v_mul_f32_e32 v2, v3, v2
	v_add_f32_e32 v3, 1.0, v20
	v_rcp_f32_e32 v3, v3
	v_add_f32_e32 v20, 1.0, v21
	v_rcp_f32_e32 v20, v20
	v_mul_f32_e32 v15, v15, v2
	v_mul_f32_e32 v2, v4, v3
	v_mul_f32_e32 v3, 0xbfb8aa3b, v6
	v_mul_f32_e32 v4, v12, v2
	v_mul_f32_e32 v2, v5, v20
	v_exp_f32_e32 v3, v3
	v_mul_f32_e32 v5, 0xbfb8aa3b, v7
	v_exp_f32_e32 v5, v5
	v_mul_f32_e32 v12, v13, v2
	v_add_f32_e32 v2, 1.0, v3
	v_rcp_f32_e32 v2, v2
	v_add_f32_e32 v3, 1.0, v5
	v_mul_f32_e32 v5, 0xbfb8aa3b, v10
	v_rcp_f32_e32 v3, v3
	v_exp_f32_e32 v5, v5
	v_mul_f32_e32 v2, v6, v2
	v_mul_f32_e32 v6, v16, v2
	v_mul_f32_e32 v2, v7, v3
	v_add_f32_e32 v3, 1.0, v5
	v_rcp_f32_e32 v3, v3
	v_mul_f32_e32 v5, 0xbfb8aa3b, v11
	v_exp_f32_e32 v5, v5
	v_mul_f32_e32 v7, v17, v2
	v_mul_f32_e32 v2, v10, v3
	v_mul_f32_e32 v10, v18, v2
	v_add_f32_e32 v2, 1.0, v5
	v_rcp_f32_e32 v5, v2
	v_mov_b32_e32 v2, 0
	v_mov_b32_e32 v3, 0
	v_cvt_scalef32_pk_fp8_f32 v2, v14, v15, s12
	v_cvt_scalef32_pk_fp8_f32 v3, v6, v7, s12
	v_mul_f32_e32 v5, v11, v5
	v_mul_f32_e32 v5, v19, v5
	v_cvt_scalef32_pk_fp8_f32 v2, v4, v12, s12 op_sel:[0,0,0,1]
	v_cvt_scalef32_pk_fp8_f32 v3, v10, v5, s12 op_sel:[0,0,0,1]
	v_lshl_add_u64 v[4:5], s[38:39], 0, v[8:9]
	global_store_dwordx2 v[4:5], v[0:1], off
	global_store_dwordx2 v[4:5], v[2:3], off offset:128
	s_cbranch_vccnz .LBB0_1037
	s_andn2_b64 vcc, exec, s[4:5]
	s_cbranch_vccnz .LBB0_1036
	s_barrier
	s_branch .LBB0_1036
